# convert_weights: both 16-load trips of each 64x32 transpose block issued back to back (32 loads in flight) in 8 of 9 instances
# speedup vs baseline: 1.0115x; 1.0017x over previous
; #define LAS __attribute__((address_space(3)))
; template <bool FINAL>
; __device__ __forceinline__ void lru_wave_phase(ArgP a, int l, LAS unsigned char* lds, int gw, int NGW, int wave, int lane, int tid) {
;     LAS float* cw = (LAS float*)(lds + LRU_CW_OFF);
;     for (int i = tid; i < 5 * 384; i += NTHR) cw[i] = i < 1536 ? a->in[12][l * 1536 + i] : a->in[13][l * 384 + (i - 1536)];
.LBB0_506:
	s_movk_i32 s77, 0x2fff
	s_mov_b32 s78, 0x3fb8aa3b
	s_branch .LBB0_261
.Ltramp_10:
	s_branch .LBB0_10
.Ltramp_9:
	s_branch .LBB0_9
.LBB0_507:
	v_readlane_b32 s0, v254, 55
	v_mbcnt_lo_u32_b32 v1, -1, 0
	v_mbcnt_hi_u32_b32 v1, -1, v1
	s_nop 1
	v_add_u32_e32 v2, s0, v1
	s_movk_i32 s0, 0x780
	v_cmp_gt_i32_e32 vcc, s0, v2
	s_and_saveexec_b64 s[0:1], vcc
	s_cbranch_execz .LBB0_510
	v_readlane_b32 s2, v254, 48
	s_lshl_b32 s2, s2, 8
	s_add_i32 s2, s2, 0
	s_mul_i32 s12, s62, 0x180
	s_add_i32 s2, s2, 0x10000
	s_addk_i32 s12, 0xfa00
	v_lshl_add_u32 v3, v1, 2, s2
	s_mov_b64 s[2:3], 0

; template <int MODE> __device__ __forceinline__ void transpose_item(const float* __restrict__ W, int N, bf16_t* __restrict__ WT, int ldk, LAS float* scr, int item, int lane) {
;     const int nblk = N / 32, kb = item / nblk, nb = item % nblk, k0 = 64 * kb, n0 = 32 * nb;
; #pragma unroll 8
;     for (int i = 0; i < 32; ++i) { const int kk = 2 * i + (lane >> 5); scr[kk * 33 + (lane & 31)] = W[(size_t)(k0 + kk) * N + n0 + (lane & 31)]; }
.LBB0_1035:
	s_lshl_b32 s28, s3, 1
	s_lshl_b32 s29, s2, 1
	v_add_u32_e32 v42, s29, v1
	v_add_u32_e32 v44, s28, v2
	v_add_u32_e32 v46, s29, v3
	v_add_u32_e32 v48, s28, v26
	v_add_u32_e32 v50, s29, v5
	v_add_u32_e32 v62, s28, v28
	v_add_u32_e32 v64, s29, v7
	v_add_u32_e32 v66, s28, v30
	v_add_u32_e32 v68, s29, v27
	v_add_u32_e32 v70, s28, v32
	v_add_u32_e32 v72, s29, v29
	v_add_u32_e32 v74, s28, v34
	v_add_u32_e32 v76, s29, v31
	v_add_u32_e32 v78, s28, v36
	v_add_u32_e32 v80, s29, v33
	v_add_u32_e32 v82, s28, v38
	v_ashrrev_i32_e32 v45, 31, v44
	v_ashrrev_i32_e32 v43, 31, v42
	v_ashrrev_i32_e32 v49, 31, v48
	v_ashrrev_i32_e32 v47, 31, v46
	v_ashrrev_i32_e32 v51, 31, v50
	v_ashrrev_i32_e32 v63, 31, v62
	v_ashrrev_i32_e32 v67, 31, v66
	v_ashrrev_i32_e32 v65, 31, v64
	v_ashrrev_i32_e32 v71, 31, v70
	v_ashrrev_i32_e32 v69, 31, v68
	v_ashrrev_i32_e32 v75, 31, v74
	v_ashrrev_i32_e32 v73, 31, v72
	v_ashrrev_i32_e32 v79, 31, v78
	v_ashrrev_i32_e32 v77, 31, v76
	v_ashrrev_i32_e32 v83, 31, v82
	v_ashrrev_i32_e32 v81, 31, v80
	v_lshlrev_b64 v[84:85], 8, v[42:43]
	v_lshlrev_b64 v[86:87], 8, v[44:45]
	v_lshlrev_b64 v[88:89], 8, v[46:47]
	v_lshlrev_b64 v[90:91], 8, v[48:49]
	v_lshlrev_b64 v[92:93], 8, v[50:51]
	v_lshlrev_b64 v[94:95], 8, v[62:63]
	v_lshlrev_b64 v[96:97], 8, v[64:65]
	v_lshlrev_b64 v[98:99], 8, v[66:67]
	v_lshlrev_b64 v[100:101], 8, v[68:69]
	v_lshlrev_b64 v[102:103], 8, v[70:71]
	v_lshlrev_b64 v[104:105], 8, v[72:73]
	v_lshlrev_b64 v[106:107], 8, v[74:75]
	v_lshlrev_b64 v[108:109], 8, v[76:77]
	v_lshlrev_b64 v[110:111], 8, v[78:79]
	v_lshlrev_b64 v[112:113], 8, v[80:81]
	v_lshlrev_b64 v[114:115], 8, v[82:83]
	v_lshl_add_u64 v[86:87], v[40:41], 0, v[86:87]
	v_lshl_add_u64 v[84:85], v[40:41], 0, v[84:85]
	v_lshl_add_u64 v[90:91], v[40:41], 0, v[90:91]
	v_lshl_add_u64 v[88:89], v[40:41], 0, v[88:89]
	v_lshl_add_u64 v[92:93], v[40:41], 0, v[92:93]
	v_lshl_add_u64 v[94:95], v[40:41], 0, v[94:95]
	v_lshl_add_u64 v[98:99], v[40:41], 0, v[98:99]
	v_lshl_add_u64 v[96:97], v[40:41], 0, v[96:97]
	v_lshl_add_u64 v[102:103], v[40:41], 0, v[102:103]
	v_lshl_add_u64 v[100:101], v[40:41], 0, v[100:101]
	v_lshl_add_u64 v[106:107], v[40:41], 0, v[106:107]
	v_lshl_add_u64 v[104:105], v[40:41], 0, v[104:105]
	v_lshl_add_u64 v[110:111], v[40:41], 0, v[110:111]
	v_lshl_add_u64 v[108:109], v[40:41], 0, v[108:109]
	v_lshl_add_u64 v[114:115], v[40:41], 0, v[114:115]
	v_lshl_add_u64 v[112:113], v[40:41], 0, v[112:113]
	global_load_dword v35, v[86:87], off
	global_load_dword v37, v[84:85], off
	global_load_dword v39, v[90:91], off
	global_load_dword v52, v[88:89], off
	global_load_dword v54, v[94:95], off
	global_load_dword v56, v[92:93], off
	global_load_dword v61, v[98:99], off
	global_load_dword v84, v[96:97], off
	global_load_dword v85, v[102:103], off
	global_load_dword v86, v[100:101], off
	global_load_dword v87, v[106:107], off
	global_load_dword v88, v[104:105], off
	global_load_dword v89, v[110:111], off
	global_load_dword v90, v[108:109], off
	global_load_dword v91, v[114:115], off
	global_load_dword v92, v[112:113], off
	s_add_i32 s3, s3, 16
	s_add_i32 s2, s2, 16
	s_add_i32 s13, s13, -16
	s_cmp_lg_u32 s13, 0
	v_mad_u64_u32 v[44:45], s[28:29], v44, s83, v[6:7]
	v_mad_u64_u32 v[42:43], s[28:29], v42, s83, v[6:7]
	v_mad_u64_u32 v[48:49], s[28:29], v48, s83, v[6:7]
	v_mad_u64_u32 v[46:47], s[28:29], v46, s83, v[6:7]
	v_mad_u64_u32 v[62:63], s[28:29], v62, s83, v[6:7]
	v_mad_u64_u32 v[50:51], s[28:29], v50, s83, v[6:7]
	v_mad_u64_u32 v[66:67], s[28:29], v66, s83, v[6:7]
	v_mad_u64_u32 v[64:65], s[28:29], v64, s83, v[6:7]
	v_mad_u64_u32 v[70:71], s[28:29], v70, s83, v[6:7]
	v_mad_u64_u32 v[68:69], s[28:29], v68, s83, v[6:7]
	v_mad_u64_u32 v[74:75], s[28:29], v74, s83, v[6:7]
	v_mad_u64_u32 v[72:73], s[28:29], v72, s83, v[6:7]
	v_mad_u64_u32 v[78:79], s[28:29], v78, s83, v[6:7]
	v_mad_u64_u32 v[76:77], s[28:29], v76, s83, v[6:7]
	v_mad_u64_u32 v[82:83], s[28:29], v82, s83, v[6:7]
	v_mad_u64_u32 v[80:81], s[28:29], v80, s83, v[6:7]
	s_lshl_b32 s28, s3, 1
	s_lshl_b32 s29, s2, 1
	v_add_u32_e32 v172, s29, v1
	v_add_u32_e32 v174, s28, v2
	v_add_u32_e32 v176, s29, v3
	v_add_u32_e32 v178, s28, v26
	v_add_u32_e32 v180, s29, v5
	v_add_u32_e32 v118, s28, v28
	v_add_u32_e32 v120, s29, v7
	v_add_u32_e32 v122, s28, v30
	v_add_u32_e32 v124, s29, v27
	v_add_u32_e32 v126, s28, v32
	v_add_u32_e32 v128, s29, v29
	v_add_u32_e32 v130, s28, v34
	v_add_u32_e32 v132, s29, v31
	v_add_u32_e32 v134, s28, v36
	v_add_u32_e32 v136, s29, v33
	v_add_u32_e32 v138, s28, v38
	v_ashrrev_i32_e32 v175, 31, v174
	v_ashrrev_i32_e32 v173, 31, v172
	v_ashrrev_i32_e32 v179, 31, v178
	v_ashrrev_i32_e32 v177, 31, v176
	v_ashrrev_i32_e32 v181, 31, v180
	v_ashrrev_i32_e32 v119, 31, v118
	v_ashrrev_i32_e32 v123, 31, v122
	v_ashrrev_i32_e32 v121, 31, v120
	v_ashrrev_i32_e32 v127, 31, v126
	v_ashrrev_i32_e32 v125, 31, v124
	v_ashrrev_i32_e32 v131, 31, v130
	v_ashrrev_i32_e32 v129, 31, v128
	v_ashrrev_i32_e32 v135, 31, v134
	v_ashrrev_i32_e32 v133, 31, v132
	v_ashrrev_i32_e32 v139, 31, v138
	v_ashrrev_i32_e32 v137, 31, v136
	v_lshlrev_b64 v[140:141], 8, v[172:173]
	v_lshlrev_b64 v[142:143], 8, v[174:175]
	v_lshlrev_b64 v[144:145], 8, v[176:177]
	v_lshlrev_b64 v[146:147], 8, v[178:179]
	v_lshlrev_b64 v[148:149], 8, v[180:181]
	v_lshlrev_b64 v[150:151], 8, v[118:119]
	v_lshlrev_b64 v[152:153], 8, v[120:121]
	v_lshlrev_b64 v[154:155], 8, v[122:123]
	v_lshlrev_b64 v[156:157], 8, v[124:125]
	v_lshlrev_b64 v[158:159], 8, v[126:127]
	v_lshlrev_b64 v[160:161], 8, v[128:129]
	v_lshlrev_b64 v[162:163], 8, v[130:131]
	v_lshlrev_b64 v[164:165], 8, v[132:133]
	v_lshlrev_b64 v[166:167], 8, v[134:135]
; #define LAS __attribute__((address_space(3)))
; __device__ __forceinline__ unsigned pk2(float lo, float hi) { return pg8::cvt_pk_bf16(lo, hi); }
; #define LDS_WAIT() asm volatile("s_waitcnt lgkmcnt(0)" ::: "memory")
; template <int MODE> __device__ __forceinline__ void transpose_item(const float* __restrict__ W, int N, bf16_t* __restrict__ WT, int ldk, LAS float* scr, int item, int lane) {
;     ...
;     for (int i = 0; i < 32; ++i) { const int kk = 2 * i + (lane >> 5); scr[kk * 33 + (lane & 31)] = W[(size_t)(k0 + kk) * N + n0 + (lane & 31)]; }
;     LDS_WAIT();
;     const int c = lane & 7, r0 = dest_row<MODE>(n0);
; #pragma unroll
;     for (int j = 0; j < 4; ++j) { const int n = (lane >> 3) + 8 * j; const LAS float* s = scr + (8 * c) * 33 + n;
;         u32x4 o; o.x = pk2(s[0 * 33], s[1 * 33]); o.y = pk2(s[2 * 33], s[3 * 33]); o.z = pk2(s[4 * 33], s[5 * 33]); o.w = pk2(s[6 * 33], s[7 * 33]);
;         *(u32x4*)(WT + (size_t)(r0 + n) * ldk + k0 + 8 * c) = o; }
;     LDS_WAIT();
	v_lshlrev_b64 v[168:169], 8, v[136:137]
	v_lshlrev_b64 v[170:171], 8, v[138:139]
	v_lshl_add_u64 v[142:143], v[40:41], 0, v[142:143]
	v_lshl_add_u64 v[140:141], v[40:41], 0, v[140:141]
	v_lshl_add_u64 v[146:147], v[40:41], 0, v[146:147]
	v_lshl_add_u64 v[144:145], v[40:41], 0, v[144:145]
	v_lshl_add_u64 v[148:149], v[40:41], 0, v[148:149]
	v_lshl_add_u64 v[150:151], v[40:41], 0, v[150:151]
	v_lshl_add_u64 v[154:155], v[40:41], 0, v[154:155]
	v_lshl_add_u64 v[152:153], v[40:41], 0, v[152:153]
	v_lshl_add_u64 v[158:159], v[40:41], 0, v[158:159]
	v_lshl_add_u64 v[156:157], v[40:41], 0, v[156:157]
	v_lshl_add_u64 v[162:163], v[40:41], 0, v[162:163]
	v_lshl_add_u64 v[160:161], v[40:41], 0, v[160:161]
	v_lshl_add_u64 v[166:167], v[40:41], 0, v[166:167]
	v_lshl_add_u64 v[164:165], v[40:41], 0, v[164:165]
	v_lshl_add_u64 v[170:171], v[40:41], 0, v[170:171]
	v_lshl_add_u64 v[168:169], v[40:41], 0, v[168:169]
	global_load_dword v183, v[142:143], off
	global_load_dword v185, v[140:141], off
	global_load_dword v187, v[146:147], off
	global_load_dword v182, v[144:145], off
	global_load_dword v116, v[150:151], off
	global_load_dword v184, v[148:149], off
	global_load_dword v117, v[154:155], off
	global_load_dword v140, v[152:153], off
	global_load_dword v141, v[158:159], off
	global_load_dword v142, v[156:157], off
	global_load_dword v143, v[162:163], off
	global_load_dword v144, v[160:161], off
	global_load_dword v145, v[166:167], off
	global_load_dword v146, v[164:165], off
	global_load_dword v147, v[170:171], off
	global_load_dword v148, v[168:169], off
	s_add_i32 s3, s3, 16
	s_add_i32 s2, s2, 16
	s_add_i32 s13, s13, -16
	s_cmp_lg_u32 s13, 0
	v_mad_u64_u32 v[174:175], s[28:29], v174, s83, v[6:7]
	v_mad_u64_u32 v[172:173], s[28:29], v172, s83, v[6:7]
	v_mad_u64_u32 v[178:179], s[28:29], v178, s83, v[6:7]
	v_mad_u64_u32 v[176:177], s[28:29], v176, s83, v[6:7]
	v_mad_u64_u32 v[118:119], s[28:29], v118, s83, v[6:7]
	v_mad_u64_u32 v[180:181], s[28:29], v180, s83, v[6:7]
	v_mad_u64_u32 v[122:123], s[28:29], v122, s83, v[6:7]
	v_mad_u64_u32 v[120:121], s[28:29], v120, s83, v[6:7]
	v_mad_u64_u32 v[126:127], s[28:29], v126, s83, v[6:7]
	v_mad_u64_u32 v[124:125], s[28:29], v124, s83, v[6:7]
	v_mad_u64_u32 v[130:131], s[28:29], v130, s83, v[6:7]
	v_mad_u64_u32 v[128:129], s[28:29], v128, s83, v[6:7]
	v_mad_u64_u32 v[134:135], s[28:29], v134, s83, v[6:7]
	v_mad_u64_u32 v[132:133], s[28:29], v132, s83, v[6:7]
	v_mad_u64_u32 v[138:139], s[28:29], v138, s83, v[6:7]
	v_mad_u64_u32 v[136:137], s[28:29], v136, s83, v[6:7]
	s_waitcnt vmcnt(16)
	ds_write_b32 v44, v35
	ds_write_b32 v42, v37
	ds_write_b32 v48, v39
	ds_write_b32 v46, v52
	ds_write_b32 v62, v54
	ds_write_b32 v50, v56
	ds_write_b32 v66, v61
	ds_write_b32 v64, v84
	ds_write_b32 v70, v85
	ds_write_b32 v68, v86
	ds_write_b32 v74, v87
	ds_write_b32 v72, v88
	ds_write_b32 v78, v89
	ds_write_b32 v76, v90
	ds_write_b32 v82, v91
	ds_write_b32 v80, v92
	s_waitcnt vmcnt(0)
	ds_write_b32 v174, v183
	ds_write_b32 v172, v185
	ds_write_b32 v178, v187
	ds_write_b32 v176, v182
	ds_write_b32 v118, v116
	ds_write_b32 v180, v184
	ds_write_b32 v122, v117
	ds_write_b32 v120, v140
	ds_write_b32 v126, v141
	ds_write_b32 v124, v142
	ds_write_b32 v130, v143
	ds_write_b32 v128, v144
	ds_write_b32 v134, v145
	ds_write_b32 v132, v146
	ds_write_b32 v138, v147
	ds_write_b32 v136, v148
	s_waitcnt lgkmcnt(0)
	ds_read2_b32 v[44:45], v57 offset0:33 offset1:41
	ds_read2_b32 v[46:47], v57 offset1:8
	ds_read2_b32 v[48:49], v57 offset0:66 offset1:74
	ds_read2_b32 v[50:51], v57 offset0:99 offset1:107
	ds_read2_b32 v[62:63], v57 offset0:132 offset1:140
	ds_read2_b32 v[64:65], v57 offset0:165 offset1:173
	ds_read2_b32 v[66:67], v57 offset0:198 offset1:206
	ds_read2_b32 v[68:69], v57 offset0:231 offset1:239
	s_and_b32 s12, 0xffff, s12
	v_add_u32_e32 v72, s12, v55
	s_lshl_b64 s[2:3], s[16:17], 13
	v_ashrrev_i32_e32 v73, 31, v72
	v_lshl_add_u64 v[70:71], v[8:9], 0, s[2:3]
	v_lshlrev_b64 v[72:73], 7, v[72:73]
	s_waitcnt lgkmcnt(6)
	v_cvt_pk_f16_f32 v40, v46, v44
	s_waitcnt lgkmcnt(4)
	v_cvt_pk_f16_f32 v41, v48, v50
	s_waitcnt lgkmcnt(2)
	v_cvt_pk_f16_f32 v42, v62, v64
	s_waitcnt lgkmcnt(0)
	v_cvt_pk_f16_f32 v43, v66, v68
	v_lshl_add_u64 v[72:73], v[70:71], 0, v[72:73]
	v_add_u32_e32 v44, s12, v58
	global_store_dwordx4 v[72:73], v[40:43], off
	s_mov_b64 s[2:3], 0
	s_nop 0
	v_cvt_pk_f16_f32 v40, v47, v45
	v_ashrrev_i32_e32 v45, 31, v44
	v_cvt_pk_f16_f32 v41, v49, v51
	v_cvt_pk_f16_f32 v42, v63, v65
	v_cvt_pk_f16_f32 v43, v67, v69
	v_lshlrev_b64 v[44:45], 7, v[44:45]
	ds_read2_b32 v[46:47], v57 offset0:49 offset1:57
	ds_read2_b32 v[48:49], v57 offset0:16 offset1:24
	ds_read2_b32 v[50:51], v57 offset0:82 offset1:90
	ds_read2_b32 v[62:63], v57 offset0:115 offset1:123
	ds_read2_b32 v[64:65], v57 offset0:148 offset1:156
	ds_read2_b32 v[66:67], v57 offset0:181 offset1:189
	ds_read2_b32 v[68:69], v57 offset0:214 offset1:222
	ds_read2_b32 v[72:73], v57 offset0:247 offset1:255
	v_lshl_add_u64 v[44:45], v[70:71], 0, v[44:45]
	global_store_dwordx4 v[44:45], v[40:43], off
	v_add_u32_e32 v44, s12, v59
	v_ashrrev_i32_e32 v45, 31, v44
	v_lshlrev_b64 v[44:45], 7, v[44:45]
	s_waitcnt lgkmcnt(6)
	v_cvt_pk_f16_f32 v40, v48, v46
	s_waitcnt lgkmcnt(4)
	v_cvt_pk_f16_f32 v41, v50, v62
	s_waitcnt lgkmcnt(2)
	v_cvt_pk_f16_f32 v42, v64, v66
	s_waitcnt lgkmcnt(0)
	v_cvt_pk_f16_f32 v43, v68, v72
	v_lshl_add_u64 v[44:45], v[70:71], 0, v[44:45]
	global_store_dwordx4 v[44:45], v[40:43], off
	v_add_u32_e32 v44, s12, v60
	v_ashrrev_i32_e32 v45, 31, v44
	v_lshlrev_b64 v[44:45], 7, v[44:45]
	v_cvt_pk_f16_f32 v40, v49, v47
	v_cvt_pk_f16_f32 v41, v51, v63
	v_cvt_pk_f16_f32 v42, v65, v67
	v_cvt_pk_f16_f32 v43, v69, v73
	v_lshl_add_u64 v[44:45], v[70:71], 0, v[44:45]
	global_store_dwordx4 v[44:45], v[40:43], off
	s_waitcnt lgkmcnt(0)

; template <int MODE> __device__ __forceinline__ void transpose_item(const float* __restrict__ W, int N, bf16_t* __restrict__ WT, int ldk, LAS float* scr, int item, int lane) {
;     const int nblk = N / 32, kb = item / nblk, nb = item % nblk, k0 = 64 * kb, n0 = 32 * nb;
; #pragma unroll 8
;     for (int i = 0; i < 32; ++i) { const int kk = 2 * i + (lane >> 5); scr[kk * 33 + (lane & 31)] = W[(size_t)(k0 + kk) * N + n0 + (lane & 31)]; }
.LBB0_1039:
	s_lshl_b32 s34, s2, 1
	s_lshl_b32 s35, s13, 1
	v_add_u32_e32 v62, s34, v42
	v_add_u32_e32 v61, s35, v35
	v_add_u32_e32 v68, s35, v37
	v_add_u32_e32 v66, s34, v44
	v_add_u32_e32 v72, s35, v39
	v_add_u32_e32 v70, s34, v46
	v_add_u32_e32 v76, s35, v43
	v_add_u32_e32 v74, s34, v48
	v_add_u32_e32 v80, s35, v45
	v_add_u32_e32 v78, s34, v50
	v_add_u32_e32 v84, s35, v47
	v_add_u32_e32 v82, s34, v52
	v_add_u32_e32 v88, s35, v49
	v_add_u32_e32 v86, s34, v54
	v_add_u32_e32 v92, s35, v51
	v_add_u32_e32 v90, s34, v56
	v_mad_i64_i32 v[62:63], s[28:29], v62, s70, v[40:41]
	v_mad_i64_i32 v[64:65], s[28:29], v61, s70, v[40:41]
	v_mad_i64_i32 v[66:67], s[28:29], v66, s70, v[40:41]
	v_mad_i64_i32 v[68:69], s[28:29], v68, s70, v[40:41]
	v_mad_i64_i32 v[70:71], s[28:29], v70, s70, v[40:41]
	v_mad_i64_i32 v[72:73], s[28:29], v72, s70, v[40:41]
	v_mad_i64_i32 v[74:75], s[28:29], v74, s70, v[40:41]
	v_mad_i64_i32 v[76:77], s[28:29], v76, s70, v[40:41]
	v_mad_i64_i32 v[78:79], s[28:29], v78, s70, v[40:41]
	v_mad_i64_i32 v[80:81], s[28:29], v80, s70, v[40:41]
	v_mad_i64_i32 v[82:83], s[28:29], v82, s70, v[40:41]
	v_mad_i64_i32 v[84:85], s[28:29], v84, s70, v[40:41]
	v_mad_i64_i32 v[86:87], s[28:29], v86, s70, v[40:41]
	v_mad_i64_i32 v[88:89], s[28:29], v88, s70, v[40:41]
	v_mad_i64_i32 v[90:91], s[28:29], v90, s70, v[40:41]
	v_mad_i64_i32 v[92:93], s[28:29], v92, s70, v[40:41]
	global_load_dword v61, v[62:63], off
	global_load_dword v94, v[64:65], off
	global_load_dword v95, v[66:67], off
	global_load_dword v96, v[68:69], off
	global_load_dword v97, v[70:71], off
	global_load_dword v98, v[72:73], off
	global_load_dword v99, v[74:75], off
	global_load_dword v100, v[76:77], off
	global_load_dword v101, v[78:79], off
	global_load_dword v102, v[80:81], off
	global_load_dword v103, v[82:83], off
	global_load_dword v104, v[84:85], off
	global_load_dword v105, v[86:87], off
	global_load_dword v106, v[88:89], off
	global_load_dword v107, v[90:91], off
	global_load_dword v108, v[92:93], off
	s_add_i32 s2, s2, 16
	s_add_i32 s13, s13, 16
	s_add_i32 s16, s16, -16
	v_add_u32_e32 v62, s34, v2
	v_add_u32_e32 v64, s35, v1
	v_add_u32_e32 v68, s35, v3
	v_add_u32_e32 v66, s34, v26
	v_add_u32_e32 v72, s35, v5
	v_add_u32_e32 v70, s34, v28
	v_add_u32_e32 v76, s35, v7
	v_add_u32_e32 v74, s34, v30
	v_add_u32_e32 v80, s35, v27
	v_add_u32_e32 v78, s34, v32
	v_add_u32_e32 v84, s35, v29
	v_add_u32_e32 v82, s34, v34
	v_add_u32_e32 v88, s35, v31
	v_add_u32_e32 v86, s34, v36
	v_add_u32_e32 v92, s35, v33
	v_add_u32_e32 v90, s34, v38
	s_cmp_lg_u32 s16, 0
	v_mad_u64_u32 v[62:63], s[28:29], v62, s83, v[6:7]
	v_mad_u64_u32 v[64:65], s[28:29], v64, s83, v[6:7]
	v_mad_u64_u32 v[66:67], s[28:29], v66, s83, v[6:7]
	v_mad_u64_u32 v[68:69], s[28:29], v68, s83, v[6:7]
	v_mad_u64_u32 v[70:71], s[28:29], v70, s83, v[6:7]
	v_mad_u64_u32 v[72:73], s[28:29], v72, s83, v[6:7]
	v_mad_u64_u32 v[74:75], s[28:29], v74, s83, v[6:7]
	v_mad_u64_u32 v[76:77], s[28:29], v76, s83, v[6:7]
	v_mad_u64_u32 v[78:79], s[28:29], v78, s83, v[6:7]
	v_mad_u64_u32 v[80:81], s[28:29], v80, s83, v[6:7]
	v_mad_u64_u32 v[82:83], s[28:29], v82, s83, v[6:7]
	v_mad_u64_u32 v[84:85], s[28:29], v84, s83, v[6:7]
	v_mad_u64_u32 v[86:87], s[28:29], v86, s83, v[6:7]
	v_mad_u64_u32 v[88:89], s[28:29], v88, s83, v[6:7]
	v_mad_u64_u32 v[90:91], s[28:29], v90, s83, v[6:7]
	v_mad_u64_u32 v[92:93], s[28:29], v92, s83, v[6:7]
	s_lshl_b32 s34, s2, 1
	s_lshl_b32 s35, s13, 1
	v_add_u32_e32 v118, s34, v42
	v_add_u32_e32 v117, s35, v35
	v_add_u32_e32 v124, s35, v37
	v_add_u32_e32 v122, s34, v44
	v_add_u32_e32 v128, s35, v39
	v_add_u32_e32 v126, s34, v46
	v_add_u32_e32 v132, s35, v43
	v_add_u32_e32 v130, s34, v48
	v_add_u32_e32 v136, s35, v45
	v_add_u32_e32 v134, s34, v50
	v_add_u32_e32 v140, s35, v47
	v_add_u32_e32 v138, s34, v52
	v_add_u32_e32 v144, s35, v49
	v_add_u32_e32 v142, s34, v54
	v_add_u32_e32 v148, s35, v51
	v_add_u32_e32 v146, s34, v56
	v_mad_i64_i32 v[118:119], s[28:29], v118, s70, v[40:41]
	v_mad_i64_i32 v[120:121], s[28:29], v117, s70, v[40:41]
	v_mad_i64_i32 v[122:123], s[28:29], v122, s70, v[40:41]
	v_mad_i64_i32 v[124:125], s[28:29], v124, s70, v[40:41]
	v_mad_i64_i32 v[126:127], s[28:29], v126, s70, v[40:41]
	v_mad_i64_i32 v[128:129], s[28:29], v128, s70, v[40:41]
	v_mad_i64_i32 v[130:131], s[28:29], v130, s70, v[40:41]
	v_mad_i64_i32 v[132:133], s[28:29], v132, s70, v[40:41]
	v_mad_i64_i32 v[134:135], s[28:29], v134, s70, v[40:41]
	v_mad_i64_i32 v[136:137], s[28:29], v136, s70, v[40:41]
	v_mad_i64_i32 v[138:139], s[28:29], v138, s70, v[40:41]
	v_mad_i64_i32 v[140:141], s[28:29], v140, s70, v[40:41]
	v_mad_i64_i32 v[142:143], s[28:29], v142, s70, v[40:41]
	v_mad_i64_i32 v[144:145], s[28:29], v144, s70, v[40:41]
	v_mad_i64_i32 v[146:147], s[28:29], v146, s70, v[40:41]
	v_mad_i64_i32 v[148:149], s[28:29], v148, s70, v[40:41]
	global_load_dword v117, v[118:119], off
	global_load_dword v150, v[120:121], off
	global_load_dword v151, v[122:123], off
	global_load_dword v152, v[124:125], off
	global_load_dword v153, v[126:127], off
	global_load_dword v154, v[128:129], off
	global_load_dword v155, v[130:131], off
	global_load_dword v156, v[132:133], off
	global_load_dword v157, v[134:135], off
	global_load_dword v158, v[136:137], off
	global_load_dword v159, v[138:139], off
	global_load_dword v160, v[140:141], off
	global_load_dword v161, v[142:143], off
	global_load_dword v162, v[144:145], off
	global_load_dword v163, v[146:147], off
	global_load_dword v164, v[148:149], off
	s_add_i32 s2, s2, 16
	s_add_i32 s13, s13, 16
	s_add_i32 s16, s16, -16
	v_add_u32_e32 v118, s34, v2
	v_add_u32_e32 v120, s35, v1
	v_add_u32_e32 v124, s35, v3
	v_add_u32_e32 v122, s34, v26
	v_add_u32_e32 v128, s35, v5
	v_add_u32_e32 v126, s34, v28
	v_add_u32_e32 v132, s35, v7
	v_add_u32_e32 v130, s34, v30
	v_add_u32_e32 v136, s35, v27
	v_add_u32_e32 v134, s34, v32
	v_add_u32_e32 v140, s35, v29
	v_add_u32_e32 v138, s34, v34
	v_add_u32_e32 v144, s35, v31
	v_add_u32_e32 v142, s34, v36
	v_add_u32_e32 v148, s35, v33
	v_add_u32_e32 v146, s34, v38
	s_cmp_lg_u32 s16, 0
	v_mad_u64_u32 v[118:119], s[28:29], v118, s83, v[6:7]
	v_mad_u64_u32 v[120:121], s[28:29], v120, s83, v[6:7]
	v_mad_u64_u32 v[122:123], s[28:29], v122, s83, v[6:7]
	v_mad_u64_u32 v[124:125], s[28:29], v124, s83, v[6:7]
	v_mad_u64_u32 v[126:127], s[28:29], v126, s83, v[6:7]
	v_mad_u64_u32 v[128:129], s[28:29], v128, s83, v[6:7]
	v_mad_u64_u32 v[130:131], s[28:29], v130, s83, v[6:7]
	v_mad_u64_u32 v[132:133], s[28:29], v132, s83, v[6:7]
	v_mad_u64_u32 v[134:135], s[28:29], v134, s83, v[6:7]
	v_mad_u64_u32 v[136:137], s[28:29], v136, s83, v[6:7]
	v_mad_u64_u32 v[138:139], s[28:29], v138, s83, v[6:7]
	v_mad_u64_u32 v[140:141], s[28:29], v140, s83, v[6:7]
	v_mad_u64_u32 v[142:143], s[28:29], v142, s83, v[6:7]
	v_mad_u64_u32 v[144:145], s[28:29], v144, s83, v[6:7]
	v_mad_u64_u32 v[146:147], s[28:29], v146, s83, v[6:7]
	v_mad_u64_u32 v[148:149], s[28:29], v148, s83, v[6:7]
	s_waitcnt vmcnt(16)
; #define LAS __attribute__((address_space(3)))
; __device__ __forceinline__ unsigned pk2(float lo, float hi) { return pg8::cvt_pk_bf16(lo, hi); }
; #define LDS_WAIT() asm volatile("s_waitcnt lgkmcnt(0)" ::: "memory")
; template <int MODE> __device__ __forceinline__ void transpose_item(const float* __restrict__ W, int N, bf16_t* __restrict__ WT, int ldk, LAS float* scr, int item, int lane) {
;     ...
;     for (int i = 0; i < 32; ++i) { const int kk = 2 * i + (lane >> 5); scr[kk * 33 + (lane & 31)] = W[(size_t)(k0 + kk) * N + n0 + (lane & 31)]; }
;     LDS_WAIT();
;     const int c = lane & 7, r0 = dest_row<MODE>(n0);
; #pragma unroll
;     for (int j = 0; j < 4; ++j) { const int n = (lane >> 3) + 8 * j; const LAS float* s = scr + (8 * c) * 33 + n;
;         u32x4 o; o.x = pk2(s[0 * 33], s[1 * 33]); o.y = pk2(s[2 * 33], s[3 * 33]); o.z = pk2(s[4 * 33], s[5 * 33]); o.w = pk2(s[6 * 33], s[7 * 33]);
;         *(u32x4*)(WT + (size_t)(r0 + n) * ldk + k0 + 8 * c) = o; }
;     LDS_WAIT();
	ds_write_b32 v62, v61
	ds_write_b32 v64, v94
	ds_write_b32 v66, v95
	ds_write_b32 v68, v96
	ds_write_b32 v70, v97
	ds_write_b32 v72, v98
	ds_write_b32 v74, v99
	ds_write_b32 v76, v100
	ds_write_b32 v78, v101
	ds_write_b32 v80, v102
	ds_write_b32 v82, v103
	ds_write_b32 v84, v104
	ds_write_b32 v86, v105
	ds_write_b32 v88, v106
	ds_write_b32 v90, v107
	ds_write_b32 v92, v108
	s_waitcnt vmcnt(0)
	ds_write_b32 v118, v117
	ds_write_b32 v120, v150
	ds_write_b32 v122, v151
	ds_write_b32 v124, v152
	ds_write_b32 v126, v153
	ds_write_b32 v128, v154
	ds_write_b32 v130, v155
	ds_write_b32 v132, v156
	ds_write_b32 v134, v157
	ds_write_b32 v136, v158
	ds_write_b32 v138, v159
	ds_write_b32 v140, v160
	ds_write_b32 v142, v161
	ds_write_b32 v144, v162
	ds_write_b32 v146, v163
	ds_write_b32 v148, v164
	s_waitcnt lgkmcnt(0)
	ds_read2_b32 v[44:45], v57 offset0:33 offset1:41
	ds_read2_b32 v[46:47], v57 offset1:8
	ds_read2_b32 v[48:49], v57 offset0:66 offset1:74
	ds_read2_b32 v[50:51], v57 offset0:99 offset1:107
	ds_read2_b32 v[62:63], v57 offset0:132 offset1:140
	ds_read2_b32 v[64:65], v57 offset0:165 offset1:173
	ds_read2_b32 v[66:67], v57 offset0:198 offset1:206
	ds_read2_b32 v[68:69], v57 offset0:231 offset1:239
	s_and_b32 s2, 0xffff, s12
	v_add_u32_e32 v72, s2, v55
	s_lshl_b32 s16, s3, 1
	v_ashrrev_i32_e32 v73, 31, v72
	v_lshl_add_u64 v[70:71], v[10:11], 0, s[16:17]
	v_lshlrev_b64 v[72:73], 9, v[72:73]
	s_waitcnt lgkmcnt(6)
	v_cvt_pk_f16_f32 v40, v46, v44
	s_waitcnt lgkmcnt(4)
	v_cvt_pk_f16_f32 v41, v48, v50
	s_waitcnt lgkmcnt(2)
	v_cvt_pk_f16_f32 v42, v62, v64
	s_waitcnt lgkmcnt(0)
	v_cvt_pk_f16_f32 v43, v66, v68
	v_lshl_add_u64 v[72:73], v[70:71], 0, v[72:73]
	v_add_u32_e32 v44, s2, v58
	global_store_dwordx4 v[72:73], v[40:43], off
	s_nop 1
	v_cvt_pk_f16_f32 v40, v47, v45
	v_ashrrev_i32_e32 v45, 31, v44
	v_cvt_pk_f16_f32 v41, v49, v51
	v_cvt_pk_f16_f32 v42, v63, v65
	v_cvt_pk_f16_f32 v43, v67, v69
	v_lshlrev_b64 v[44:45], 9, v[44:45]
	ds_read2_b32 v[46:47], v57 offset0:49 offset1:57
	ds_read2_b32 v[48:49], v57 offset0:16 offset1:24
	ds_read2_b32 v[50:51], v57 offset0:82 offset1:90
	ds_read2_b32 v[62:63], v57 offset0:115 offset1:123
	ds_read2_b32 v[64:65], v57 offset0:148 offset1:156
	ds_read2_b32 v[66:67], v57 offset0:181 offset1:189
	ds_read2_b32 v[68:69], v57 offset0:214 offset1:222
	ds_read2_b32 v[72:73], v57 offset0:247 offset1:255
	v_lshl_add_u64 v[44:45], v[70:71], 0, v[44:45]
	global_store_dwordx4 v[44:45], v[40:43], off
	v_add_u32_e32 v44, s2, v59
	v_ashrrev_i32_e32 v45, 31, v44
	v_lshlrev_b64 v[44:45], 9, v[44:45]
	s_waitcnt lgkmcnt(6)
	v_cvt_pk_f16_f32 v40, v48, v46
	s_waitcnt lgkmcnt(4)
	v_cvt_pk_f16_f32 v41, v50, v62
	s_waitcnt lgkmcnt(2)
	v_cvt_pk_f16_f32 v42, v64, v66
	s_waitcnt lgkmcnt(0)
	v_cvt_pk_f16_f32 v43, v68, v72
	v_lshl_add_u64 v[44:45], v[70:71], 0, v[44:45]
	global_store_dwordx4 v[44:45], v[40:43], off
	v_add_u32_e32 v44, s2, v60
	v_ashrrev_i32_e32 v45, 31, v44
	v_lshlrev_b64 v[44:45], 9, v[44:45]
	v_cvt_pk_f16_f32 v40, v49, v47
	v_cvt_pk_f16_f32 v41, v51, v63
	v_cvt_pk_f16_f32 v42, v65, v67
	v_cvt_pk_f16_f32 v43, v69, v73
	v_lshl_add_u64 v[44:45], v[70:71], 0, v[44:45]
	global_store_dwordx4 v[44:45], v[40:43], off
	s_waitcnt lgkmcnt(0)

; template <int MODE> __device__ __forceinline__ void transpose_item(const float* __restrict__ W, int N, bf16_t* __restrict__ WT, int ldk, LAS float* scr, int item, int lane) {
;     const int nblk = N / 32, kb = item / nblk, nb = item % nblk, k0 = 64 * kb, n0 = 32 * nb;
; #pragma unroll 8
;     for (int i = 0; i < 32; ++i) { const int kk = 2 * i + (lane >> 5); scr[kk * 33 + (lane & 31)] = W[(size_t)(k0 + kk) * N + n0 + (lane & 31)]; }
.LBB0_1044:
	s_lshl_b32 s34, s13, 1
	s_lshl_b32 s35, s12, 1
	v_add_u32_e32 v62, s34, v42
	v_add_u32_e32 v61, s35, v35
	v_add_u32_e32 v68, s35, v37
	v_add_u32_e32 v66, s34, v44
	v_add_u32_e32 v72, s35, v39
	v_add_u32_e32 v70, s34, v46
	v_add_u32_e32 v76, s35, v43
	v_add_u32_e32 v74, s34, v48
	v_add_u32_e32 v80, s35, v45
	v_add_u32_e32 v78, s34, v50
	v_add_u32_e32 v84, s35, v47
	v_add_u32_e32 v82, s34, v52
	v_add_u32_e32 v88, s35, v49
	v_add_u32_e32 v86, s34, v54
	v_add_u32_e32 v92, s35, v51
	v_add_u32_e32 v90, s34, v56
	v_mad_i64_i32 v[62:63], s[28:29], v62, s68, v[40:41]
	v_mad_i64_i32 v[64:65], s[28:29], v61, s68, v[40:41]
	v_mad_i64_i32 v[66:67], s[28:29], v66, s68, v[40:41]
	v_mad_i64_i32 v[68:69], s[28:29], v68, s68, v[40:41]
	v_mad_i64_i32 v[70:71], s[28:29], v70, s68, v[40:41]
	v_mad_i64_i32 v[72:73], s[28:29], v72, s68, v[40:41]
	v_mad_i64_i32 v[74:75], s[28:29], v74, s68, v[40:41]
	v_mad_i64_i32 v[76:77], s[28:29], v76, s68, v[40:41]
	v_mad_i64_i32 v[78:79], s[28:29], v78, s68, v[40:41]
	v_mad_i64_i32 v[80:81], s[28:29], v80, s68, v[40:41]
	v_mad_i64_i32 v[82:83], s[28:29], v82, s68, v[40:41]
	v_mad_i64_i32 v[84:85], s[28:29], v84, s68, v[40:41]
	v_mad_i64_i32 v[86:87], s[28:29], v86, s68, v[40:41]
	v_mad_i64_i32 v[88:89], s[28:29], v88, s68, v[40:41]
	v_mad_i64_i32 v[90:91], s[28:29], v90, s68, v[40:41]
	v_mad_i64_i32 v[92:93], s[28:29], v92, s68, v[40:41]
	global_load_dword v61, v[62:63], off
	global_load_dword v94, v[64:65], off
	global_load_dword v95, v[66:67], off
	global_load_dword v96, v[68:69], off
	global_load_dword v97, v[70:71], off
	global_load_dword v98, v[72:73], off
	global_load_dword v99, v[74:75], off
	global_load_dword v100, v[76:77], off
	global_load_dword v101, v[78:79], off
	global_load_dword v102, v[80:81], off
	global_load_dword v103, v[82:83], off
	global_load_dword v104, v[84:85], off
	global_load_dword v105, v[86:87], off
	global_load_dword v106, v[88:89], off
	global_load_dword v107, v[90:91], off
	global_load_dword v108, v[92:93], off
	s_add_i32 s13, s13, 16
	s_add_i32 s12, s12, 16
	s_add_i32 s16, s16, -16
	v_add_u32_e32 v62, s34, v2
	v_add_u32_e32 v64, s35, v1
	v_add_u32_e32 v68, s35, v3
	v_add_u32_e32 v66, s34, v26
	v_add_u32_e32 v72, s35, v5
	v_add_u32_e32 v70, s34, v28
	v_add_u32_e32 v76, s35, v7
	v_add_u32_e32 v74, s34, v30
	v_add_u32_e32 v80, s35, v27
	v_add_u32_e32 v78, s34, v32
	v_add_u32_e32 v84, s35, v29
	v_add_u32_e32 v82, s34, v34
	v_add_u32_e32 v88, s35, v31
	v_add_u32_e32 v86, s34, v36
	v_add_u32_e32 v92, s35, v33
	v_add_u32_e32 v90, s34, v38
	s_cmp_lg_u32 s16, 0
	v_mad_u64_u32 v[62:63], s[28:29], v62, s83, v[6:7]
	v_mad_u64_u32 v[64:65], s[28:29], v64, s83, v[6:7]
	v_mad_u64_u32 v[66:67], s[28:29], v66, s83, v[6:7]
	v_mad_u64_u32 v[68:69], s[28:29], v68, s83, v[6:7]
	v_mad_u64_u32 v[70:71], s[28:29], v70, s83, v[6:7]
	v_mad_u64_u32 v[72:73], s[28:29], v72, s83, v[6:7]
	v_mad_u64_u32 v[74:75], s[28:29], v74, s83, v[6:7]
	v_mad_u64_u32 v[76:77], s[28:29], v76, s83, v[6:7]
	v_mad_u64_u32 v[78:79], s[28:29], v78, s83, v[6:7]
	v_mad_u64_u32 v[80:81], s[28:29], v80, s83, v[6:7]
	v_mad_u64_u32 v[82:83], s[28:29], v82, s83, v[6:7]
	v_mad_u64_u32 v[84:85], s[28:29], v84, s83, v[6:7]
	v_mad_u64_u32 v[86:87], s[28:29], v86, s83, v[6:7]
	v_mad_u64_u32 v[88:89], s[28:29], v88, s83, v[6:7]
	v_mad_u64_u32 v[90:91], s[28:29], v90, s83, v[6:7]
	v_mad_u64_u32 v[92:93], s[28:29], v92, s83, v[6:7]
	s_lshl_b32 s34, s13, 1
	s_lshl_b32 s35, s12, 1
	v_add_u32_e32 v118, s34, v42
	v_add_u32_e32 v117, s35, v35
	v_add_u32_e32 v124, s35, v37
	v_add_u32_e32 v122, s34, v44
	v_add_u32_e32 v128, s35, v39
	v_add_u32_e32 v126, s34, v46
	v_add_u32_e32 v132, s35, v43
	v_add_u32_e32 v130, s34, v48
	v_add_u32_e32 v136, s35, v45
	v_add_u32_e32 v134, s34, v50
	v_add_u32_e32 v140, s35, v47
	v_add_u32_e32 v138, s34, v52
	v_add_u32_e32 v144, s35, v49
	v_add_u32_e32 v142, s34, v54
	v_add_u32_e32 v148, s35, v51
	v_add_u32_e32 v146, s34, v56
	v_mad_i64_i32 v[118:119], s[28:29], v118, s68, v[40:41]
	v_mad_i64_i32 v[120:121], s[28:29], v117, s68, v[40:41]
	v_mad_i64_i32 v[122:123], s[28:29], v122, s68, v[40:41]
	v_mad_i64_i32 v[124:125], s[28:29], v124, s68, v[40:41]
	v_mad_i64_i32 v[126:127], s[28:29], v126, s68, v[40:41]
	v_mad_i64_i32 v[128:129], s[28:29], v128, s68, v[40:41]
	v_mad_i64_i32 v[130:131], s[28:29], v130, s68, v[40:41]
	v_mad_i64_i32 v[132:133], s[28:29], v132, s68, v[40:41]
	v_mad_i64_i32 v[134:135], s[28:29], v134, s68, v[40:41]
	v_mad_i64_i32 v[136:137], s[28:29], v136, s68, v[40:41]
	v_mad_i64_i32 v[138:139], s[28:29], v138, s68, v[40:41]
	v_mad_i64_i32 v[140:141], s[28:29], v140, s68, v[40:41]
	v_mad_i64_i32 v[142:143], s[28:29], v142, s68, v[40:41]
	v_mad_i64_i32 v[144:145], s[28:29], v144, s68, v[40:41]
	v_mad_i64_i32 v[146:147], s[28:29], v146, s68, v[40:41]
	v_mad_i64_i32 v[148:149], s[28:29], v148, s68, v[40:41]
	global_load_dword v117, v[118:119], off
	global_load_dword v150, v[120:121], off
	global_load_dword v151, v[122:123], off
	global_load_dword v152, v[124:125], off
	global_load_dword v153, v[126:127], off
	global_load_dword v154, v[128:129], off
	global_load_dword v155, v[130:131], off
	global_load_dword v156, v[132:133], off
	global_load_dword v157, v[134:135], off
	global_load_dword v158, v[136:137], off
	global_load_dword v159, v[138:139], off
	global_load_dword v160, v[140:141], off
	global_load_dword v161, v[142:143], off
	global_load_dword v162, v[144:145], off
	global_load_dword v163, v[146:147], off
	global_load_dword v164, v[148:149], off
	s_add_i32 s13, s13, 16
	s_add_i32 s12, s12, 16
	s_add_i32 s16, s16, -16
	v_add_u32_e32 v118, s34, v2
	v_add_u32_e32 v120, s35, v1
	v_add_u32_e32 v124, s35, v3
	v_add_u32_e32 v122, s34, v26
	v_add_u32_e32 v128, s35, v5
	v_add_u32_e32 v126, s34, v28
	v_add_u32_e32 v132, s35, v7
	v_add_u32_e32 v130, s34, v30
	v_add_u32_e32 v136, s35, v27
	v_add_u32_e32 v134, s34, v32
	v_add_u32_e32 v140, s35, v29
	v_add_u32_e32 v138, s34, v34
	v_add_u32_e32 v144, s35, v31
	v_add_u32_e32 v142, s34, v36
	v_add_u32_e32 v148, s35, v33
	v_add_u32_e32 v146, s34, v38
	s_cmp_lg_u32 s16, 0
	v_mad_u64_u32 v[118:119], s[28:29], v118, s83, v[6:7]
	v_mad_u64_u32 v[120:121], s[28:29], v120, s83, v[6:7]
	v_mad_u64_u32 v[122:123], s[28:29], v122, s83, v[6:7]
	v_mad_u64_u32 v[124:125], s[28:29], v124, s83, v[6:7]
	v_mad_u64_u32 v[126:127], s[28:29], v126, s83, v[6:7]
	v_mad_u64_u32 v[128:129], s[28:29], v128, s83, v[6:7]
	v_mad_u64_u32 v[130:131], s[28:29], v130, s83, v[6:7]
	v_mad_u64_u32 v[132:133], s[28:29], v132, s83, v[6:7]
	v_mad_u64_u32 v[134:135], s[28:29], v134, s83, v[6:7]
	v_mad_u64_u32 v[136:137], s[28:29], v136, s83, v[6:7]
	v_mad_u64_u32 v[138:139], s[28:29], v138, s83, v[6:7]
	v_mad_u64_u32 v[140:141], s[28:29], v140, s83, v[6:7]
	v_mad_u64_u32 v[142:143], s[28:29], v142, s83, v[6:7]
	v_mad_u64_u32 v[144:145], s[28:29], v144, s83, v[6:7]
	v_mad_u64_u32 v[146:147], s[28:29], v146, s83, v[6:7]
	v_mad_u64_u32 v[148:149], s[28:29], v148, s83, v[6:7]
	s_waitcnt vmcnt(16)
; #define LAS __attribute__((address_space(3)))
; __device__ __forceinline__ unsigned pk2(float lo, float hi) { return pg8::cvt_pk_bf16(lo, hi); }
; #define LDS_WAIT() asm volatile("s_waitcnt lgkmcnt(0)" ::: "memory")
; template <int MODE> __device__ __forceinline__ void transpose_item(const float* __restrict__ W, int N, bf16_t* __restrict__ WT, int ldk, LAS float* scr, int item, int lane) {
;     ...
;     for (int i = 0; i < 32; ++i) { const int kk = 2 * i + (lane >> 5); scr[kk * 33 + (lane & 31)] = W[(size_t)(k0 + kk) * N + n0 + (lane & 31)]; }
;     LDS_WAIT();
;     const int c = lane & 7, r0 = dest_row<MODE>(n0);
; #pragma unroll
;     for (int j = 0; j < 4; ++j) { const int n = (lane >> 3) + 8 * j; const LAS float* s = scr + (8 * c) * 33 + n;
;         u32x4 o; o.x = pk2(s[0 * 33], s[1 * 33]); o.y = pk2(s[2 * 33], s[3 * 33]); o.z = pk2(s[4 * 33], s[5 * 33]); o.w = pk2(s[6 * 33], s[7 * 33]);
;         *(u32x4*)(WT + (size_t)(r0 + n) * ldk + k0 + 8 * c) = o; }
;     LDS_WAIT();
	ds_write_b32 v62, v61
	ds_write_b32 v64, v94
	ds_write_b32 v66, v95
	ds_write_b32 v68, v96
	ds_write_b32 v70, v97
	ds_write_b32 v72, v98
	ds_write_b32 v74, v99
	ds_write_b32 v76, v100
	ds_write_b32 v78, v101
	ds_write_b32 v80, v102
	ds_write_b32 v82, v103
	ds_write_b32 v84, v104
	ds_write_b32 v86, v105
	ds_write_b32 v88, v106
	ds_write_b32 v90, v107
	ds_write_b32 v92, v108
	s_waitcnt vmcnt(0)
	ds_write_b32 v118, v117
	ds_write_b32 v120, v150
	ds_write_b32 v122, v151
	ds_write_b32 v124, v152
	ds_write_b32 v126, v153
	ds_write_b32 v128, v154
	ds_write_b32 v130, v155
	ds_write_b32 v132, v156
	ds_write_b32 v134, v157
	ds_write_b32 v136, v158
	ds_write_b32 v138, v159
	ds_write_b32 v140, v160
	ds_write_b32 v142, v161
	ds_write_b32 v144, v162
	ds_write_b32 v146, v163
	ds_write_b32 v148, v164
	s_waitcnt lgkmcnt(0)
	ds_read2_b32 v[44:45], v57 offset0:33 offset1:41
	ds_read2_b32 v[46:47], v57 offset1:8
	ds_read2_b32 v[48:49], v57 offset0:66 offset1:74
	ds_read2_b32 v[50:51], v57 offset0:99 offset1:107
	ds_read2_b32 v[62:63], v57 offset0:132 offset1:140
	ds_read2_b32 v[64:65], v57 offset0:165 offset1:173
	ds_read2_b32 v[66:67], v57 offset0:198 offset1:206
	ds_read2_b32 v[68:69], v57 offset0:231 offset1:239
	s_and_b32 s3, 0xffff, s3
	v_add_u32_e32 v72, s3, v55
	s_lshl_b32 s16, s2, 1
	v_ashrrev_i32_e32 v73, 31, v72
	v_lshl_add_u64 v[70:71], v[12:13], 0, s[16:17]
	v_lshlrev_b64 v[72:73], 9, v[72:73]
	s_waitcnt lgkmcnt(6)
	v_cvt_pk_f16_f32 v40, v46, v44
	s_waitcnt lgkmcnt(4)
	v_cvt_pk_f16_f32 v41, v48, v50
	s_waitcnt lgkmcnt(2)
	v_cvt_pk_f16_f32 v42, v62, v64
	s_waitcnt lgkmcnt(0)
	v_cvt_pk_f16_f32 v43, v66, v68
	v_lshl_add_u64 v[72:73], v[70:71], 0, v[72:73]
	v_add_u32_e32 v44, s3, v58
	global_store_dwordx4 v[72:73], v[40:43], off
	s_nop 1
	v_cvt_pk_f16_f32 v40, v47, v45
	v_ashrrev_i32_e32 v45, 31, v44
	v_cvt_pk_f16_f32 v41, v49, v51
	v_cvt_pk_f16_f32 v42, v63, v65
	v_cvt_pk_f16_f32 v43, v67, v69
	v_lshlrev_b64 v[44:45], 9, v[44:45]
	ds_read2_b32 v[46:47], v57 offset0:49 offset1:57
	ds_read2_b32 v[48:49], v57 offset0:16 offset1:24
	ds_read2_b32 v[50:51], v57 offset0:82 offset1:90
	ds_read2_b32 v[62:63], v57 offset0:115 offset1:123
	ds_read2_b32 v[64:65], v57 offset0:148 offset1:156
	ds_read2_b32 v[66:67], v57 offset0:181 offset1:189
	ds_read2_b32 v[68:69], v57 offset0:214 offset1:222
	ds_read2_b32 v[72:73], v57 offset0:247 offset1:255
	v_lshl_add_u64 v[44:45], v[70:71], 0, v[44:45]
	global_store_dwordx4 v[44:45], v[40:43], off
	v_add_u32_e32 v44, s3, v59
	v_ashrrev_i32_e32 v45, 31, v44
	v_lshlrev_b64 v[44:45], 9, v[44:45]
	s_waitcnt lgkmcnt(6)
	v_cvt_pk_f16_f32 v40, v48, v46
	s_waitcnt lgkmcnt(4)
	v_cvt_pk_f16_f32 v41, v50, v62
	s_waitcnt lgkmcnt(2)
	v_cvt_pk_f16_f32 v42, v64, v66
	s_waitcnt lgkmcnt(0)
	v_cvt_pk_f16_f32 v43, v68, v72
	v_lshl_add_u64 v[44:45], v[70:71], 0, v[44:45]
	global_store_dwordx4 v[44:45], v[40:43], off
	v_add_u32_e32 v44, s3, v60
	v_ashrrev_i32_e32 v45, 31, v44
	v_lshlrev_b64 v[44:45], 9, v[44:45]
	v_cvt_pk_f16_f32 v40, v49, v47
	v_cvt_pk_f16_f32 v41, v51, v63
	v_cvt_pk_f16_f32 v42, v65, v67
	v_cvt_pk_f16_f32 v43, v69, v73
	v_lshl_add_u64 v[44:45], v[70:71], 0, v[44:45]
	global_store_dwordx4 v[44:45], v[40:43], off
	s_waitcnt lgkmcnt(0)

; template <int MODE> __device__ __forceinline__ void transpose_item(const float* __restrict__ W, int N, bf16_t* __restrict__ WT, int ldk, LAS float* scr, int item, int lane) {
;     const int nblk = N / 32, kb = item / nblk, nb = item % nblk, k0 = 64 * kb, n0 = 32 * nb;
; #pragma unroll 8
;     for (int i = 0; i < 32; ++i) { const int kk = 2 * i + (lane >> 5); scr[kk * 33 + (lane & 31)] = W[(size_t)(k0 + kk) * N + n0 + (lane & 31)]; }
.LBB0_1049:
	s_lshl_b32 s28, s13, 1
	s_lshl_b32 s29, s2, 1
	v_add_u32_e32 v64, s28, v42
	v_add_u32_e32 v62, s29, v35
	v_add_u32_e32 v66, s29, v37
	v_add_u32_e32 v68, s28, v44
	v_add_u32_e32 v70, s29, v39
	v_add_u32_e32 v72, s28, v46
	v_add_u32_e32 v74, s29, v43
	v_add_u32_e32 v76, s28, v48
	v_add_u32_e32 v78, s29, v45
	v_add_u32_e32 v80, s28, v50
	v_add_u32_e32 v82, s29, v47
	v_add_u32_e32 v84, s28, v52
	v_add_u32_e32 v86, s29, v49
	v_add_u32_e32 v88, s28, v54
	v_add_u32_e32 v90, s29, v51
	v_add_u32_e32 v92, s28, v56
	v_ashrrev_i32_e32 v65, 31, v64
	v_ashrrev_i32_e32 v63, 31, v62
	v_ashrrev_i32_e32 v69, 31, v68
	v_ashrrev_i32_e32 v67, 31, v66
	v_ashrrev_i32_e32 v73, 31, v72
	v_ashrrev_i32_e32 v71, 31, v70
	v_ashrrev_i32_e32 v77, 31, v76
	v_ashrrev_i32_e32 v75, 31, v74
	v_ashrrev_i32_e32 v81, 31, v80
	v_ashrrev_i32_e32 v79, 31, v78
	v_ashrrev_i32_e32 v85, 31, v84
	v_ashrrev_i32_e32 v83, 31, v82
	v_ashrrev_i32_e32 v89, 31, v88
	v_ashrrev_i32_e32 v87, 31, v86
	v_ashrrev_i32_e32 v93, 31, v92
	v_ashrrev_i32_e32 v91, 31, v90
	v_lshlrev_b64 v[64:65], 12, v[64:65]
	v_lshlrev_b64 v[62:63], 12, v[62:63]
	v_lshlrev_b64 v[66:67], 12, v[66:67]
	v_lshlrev_b64 v[68:69], 12, v[68:69]
	v_lshlrev_b64 v[70:71], 12, v[70:71]
	v_lshlrev_b64 v[72:73], 12, v[72:73]
	v_lshlrev_b64 v[74:75], 12, v[74:75]
	v_lshlrev_b64 v[76:77], 12, v[76:77]
	v_lshlrev_b64 v[78:79], 12, v[78:79]
	v_lshlrev_b64 v[80:81], 12, v[80:81]
	v_lshlrev_b64 v[82:83], 12, v[82:83]
	v_lshlrev_b64 v[84:85], 12, v[84:85]
	v_lshlrev_b64 v[86:87], 12, v[86:87]
	v_lshlrev_b64 v[88:89], 12, v[88:89]
	v_lshlrev_b64 v[90:91], 12, v[90:91]
	v_lshlrev_b64 v[92:93], 12, v[92:93]
	v_lshl_add_u64 v[64:65], v[40:41], 0, v[64:65]
	v_lshl_add_u64 v[62:63], v[40:41], 0, v[62:63]
	v_lshl_add_u64 v[68:69], v[40:41], 0, v[68:69]
	v_lshl_add_u64 v[66:67], v[40:41], 0, v[66:67]
	v_lshl_add_u64 v[72:73], v[40:41], 0, v[72:73]
	v_lshl_add_u64 v[70:71], v[40:41], 0, v[70:71]
	v_lshl_add_u64 v[76:77], v[40:41], 0, v[76:77]
	v_lshl_add_u64 v[74:75], v[40:41], 0, v[74:75]
	v_lshl_add_u64 v[80:81], v[40:41], 0, v[80:81]
	v_lshl_add_u64 v[78:79], v[40:41], 0, v[78:79]
	v_lshl_add_u64 v[84:85], v[40:41], 0, v[84:85]
	v_lshl_add_u64 v[82:83], v[40:41], 0, v[82:83]
	v_lshl_add_u64 v[88:89], v[40:41], 0, v[88:89]
	v_lshl_add_u64 v[86:87], v[40:41], 0, v[86:87]
	v_lshl_add_u64 v[92:93], v[40:41], 0, v[92:93]
	v_lshl_add_u64 v[90:91], v[40:41], 0, v[90:91]
	global_load_dword v61, v[64:65], off
	global_load_dword v94, v[62:63], off
	global_load_dword v95, v[68:69], off
	global_load_dword v96, v[66:67], off
	global_load_dword v97, v[72:73], off
	global_load_dword v98, v[70:71], off
	global_load_dword v99, v[76:77], off
	global_load_dword v100, v[74:75], off
	global_load_dword v101, v[80:81], off
	global_load_dword v102, v[78:79], off
	global_load_dword v103, v[84:85], off
	global_load_dword v104, v[82:83], off
	global_load_dword v105, v[88:89], off
	global_load_dword v106, v[86:87], off
	global_load_dword v107, v[92:93], off
	global_load_dword v108, v[90:91], off
	s_add_i32 s13, s13, 16
	s_add_i32 s2, s2, 16
	s_add_i32 s16, s16, -16
	v_add_u32_e32 v62, s28, v2
	v_add_u32_e32 v64, s29, v1
	v_add_u32_e32 v68, s29, v3
	v_add_u32_e32 v66, s28, v26
	v_add_u32_e32 v72, s29, v5
	v_add_u32_e32 v70, s28, v28
	v_add_u32_e32 v76, s29, v7
	v_add_u32_e32 v74, s28, v30
	v_add_u32_e32 v80, s29, v27
	v_add_u32_e32 v78, s28, v32
	v_add_u32_e32 v84, s29, v29
	v_add_u32_e32 v82, s28, v34
	v_add_u32_e32 v88, s29, v31
	v_add_u32_e32 v86, s28, v36
	v_add_u32_e32 v92, s29, v33
	v_add_u32_e32 v90, s28, v38
	s_cmp_lg_u32 s16, 0
	v_mad_u64_u32 v[62:63], s[28:29], v62, s83, v[6:7]
	v_mad_u64_u32 v[64:65], s[28:29], v64, s83, v[6:7]
	v_mad_u64_u32 v[66:67], s[28:29], v66, s83, v[6:7]
	v_mad_u64_u32 v[68:69], s[28:29], v68, s83, v[6:7]
	v_mad_u64_u32 v[70:71], s[28:29], v70, s83, v[6:7]
	v_mad_u64_u32 v[72:73], s[28:29], v72, s83, v[6:7]
	v_mad_u64_u32 v[74:75], s[28:29], v74, s83, v[6:7]
	v_mad_u64_u32 v[76:77], s[28:29], v76, s83, v[6:7]
	v_mad_u64_u32 v[78:79], s[28:29], v78, s83, v[6:7]
	v_mad_u64_u32 v[80:81], s[28:29], v80, s83, v[6:7]
	v_mad_u64_u32 v[82:83], s[28:29], v82, s83, v[6:7]
	v_mad_u64_u32 v[84:85], s[28:29], v84, s83, v[6:7]
	v_mad_u64_u32 v[86:87], s[28:29], v86, s83, v[6:7]
	v_mad_u64_u32 v[88:89], s[28:29], v88, s83, v[6:7]
	v_mad_u64_u32 v[90:91], s[28:29], v90, s83, v[6:7]
	v_mad_u64_u32 v[92:93], s[28:29], v92, s83, v[6:7]
	s_lshl_b32 s28, s13, 1
	s_lshl_b32 s29, s2, 1
	v_add_u32_e32 v120, s28, v42
	v_add_u32_e32 v118, s29, v35
	v_add_u32_e32 v122, s29, v37
	v_add_u32_e32 v124, s28, v44
	v_add_u32_e32 v126, s29, v39
	v_add_u32_e32 v128, s28, v46
	v_add_u32_e32 v130, s29, v43
	v_add_u32_e32 v132, s28, v48
	v_add_u32_e32 v134, s29, v45
	v_add_u32_e32 v136, s28, v50
	v_add_u32_e32 v138, s29, v47
	v_add_u32_e32 v140, s28, v52
	v_add_u32_e32 v142, s29, v49
	v_add_u32_e32 v144, s28, v54
	v_add_u32_e32 v146, s29, v51
	v_add_u32_e32 v148, s28, v56
	v_ashrrev_i32_e32 v121, 31, v120
	v_ashrrev_i32_e32 v119, 31, v118
	v_ashrrev_i32_e32 v125, 31, v124
	v_ashrrev_i32_e32 v123, 31, v122
	v_ashrrev_i32_e32 v129, 31, v128
	v_ashrrev_i32_e32 v127, 31, v126
	v_ashrrev_i32_e32 v133, 31, v132
	v_ashrrev_i32_e32 v131, 31, v130
	v_ashrrev_i32_e32 v137, 31, v136
	v_ashrrev_i32_e32 v135, 31, v134
	v_ashrrev_i32_e32 v141, 31, v140
	v_ashrrev_i32_e32 v139, 31, v138
	v_ashrrev_i32_e32 v145, 31, v144
	v_ashrrev_i32_e32 v143, 31, v142
	v_ashrrev_i32_e32 v149, 31, v148
	v_ashrrev_i32_e32 v147, 31, v146
	v_lshlrev_b64 v[120:121], 12, v[120:121]
	v_lshlrev_b64 v[118:119], 12, v[118:119]
	v_lshlrev_b64 v[122:123], 12, v[122:123]
	v_lshlrev_b64 v[124:125], 12, v[124:125]
; #define LAS __attribute__((address_space(3)))
; __device__ __forceinline__ unsigned pk2(float lo, float hi) { return pg8::cvt_pk_bf16(lo, hi); }
; #define LDS_WAIT() asm volatile("s_waitcnt lgkmcnt(0)" ::: "memory")
; template <int MODE> __device__ __forceinline__ void transpose_item(const float* __restrict__ W, int N, bf16_t* __restrict__ WT, int ldk, LAS float* scr, int item, int lane) {
;     ...
;     for (int i = 0; i < 32; ++i) { const int kk = 2 * i + (lane >> 5); scr[kk * 33 + (lane & 31)] = W[(size_t)(k0 + kk) * N + n0 + (lane & 31)]; }
;     LDS_WAIT();
;     const int c = lane & 7, r0 = dest_row<MODE>(n0);
; #pragma unroll
;     for (int j = 0; j < 4; ++j) { const int n = (lane >> 3) + 8 * j; const LAS float* s = scr + (8 * c) * 33 + n;
;         u32x4 o; o.x = pk2(s[0 * 33], s[1 * 33]); o.y = pk2(s[2 * 33], s[3 * 33]); o.z = pk2(s[4 * 33], s[5 * 33]); o.w = pk2(s[6 * 33], s[7 * 33]);
;         *(u32x4*)(WT + (size_t)(r0 + n) * ldk + k0 + 8 * c) = o; }
;     LDS_WAIT();
	v_lshlrev_b64 v[126:127], 12, v[126:127]
	v_lshlrev_b64 v[128:129], 12, v[128:129]
	v_lshlrev_b64 v[130:131], 12, v[130:131]
	v_lshlrev_b64 v[132:133], 12, v[132:133]
	v_lshlrev_b64 v[134:135], 12, v[134:135]
	v_lshlrev_b64 v[136:137], 12, v[136:137]
	v_lshlrev_b64 v[138:139], 12, v[138:139]
	v_lshlrev_b64 v[140:141], 12, v[140:141]
	v_lshlrev_b64 v[142:143], 12, v[142:143]
	v_lshlrev_b64 v[144:145], 12, v[144:145]
	v_lshlrev_b64 v[146:147], 12, v[146:147]
	v_lshlrev_b64 v[148:149], 12, v[148:149]
	v_lshl_add_u64 v[120:121], v[40:41], 0, v[120:121]
	v_lshl_add_u64 v[118:119], v[40:41], 0, v[118:119]
	v_lshl_add_u64 v[124:125], v[40:41], 0, v[124:125]
	v_lshl_add_u64 v[122:123], v[40:41], 0, v[122:123]
	v_lshl_add_u64 v[128:129], v[40:41], 0, v[128:129]
	v_lshl_add_u64 v[126:127], v[40:41], 0, v[126:127]
	v_lshl_add_u64 v[132:133], v[40:41], 0, v[132:133]
	v_lshl_add_u64 v[130:131], v[40:41], 0, v[130:131]
	v_lshl_add_u64 v[136:137], v[40:41], 0, v[136:137]
	v_lshl_add_u64 v[134:135], v[40:41], 0, v[134:135]
	v_lshl_add_u64 v[140:141], v[40:41], 0, v[140:141]
	v_lshl_add_u64 v[138:139], v[40:41], 0, v[138:139]
	v_lshl_add_u64 v[144:145], v[40:41], 0, v[144:145]
	v_lshl_add_u64 v[142:143], v[40:41], 0, v[142:143]
	v_lshl_add_u64 v[148:149], v[40:41], 0, v[148:149]
	v_lshl_add_u64 v[146:147], v[40:41], 0, v[146:147]
	global_load_dword v117, v[120:121], off
	global_load_dword v150, v[118:119], off
	global_load_dword v151, v[124:125], off
	global_load_dword v152, v[122:123], off
	global_load_dword v153, v[128:129], off
	global_load_dword v154, v[126:127], off
	global_load_dword v155, v[132:133], off
	global_load_dword v156, v[130:131], off
	global_load_dword v157, v[136:137], off
	global_load_dword v158, v[134:135], off
	global_load_dword v159, v[140:141], off
	global_load_dword v160, v[138:139], off
	global_load_dword v161, v[144:145], off
	global_load_dword v162, v[142:143], off
	global_load_dword v163, v[148:149], off
	global_load_dword v164, v[146:147], off
	s_add_i32 s13, s13, 16
	s_add_i32 s2, s2, 16
	s_add_i32 s16, s16, -16
	v_add_u32_e32 v118, s28, v2
	v_add_u32_e32 v120, s29, v1
	v_add_u32_e32 v124, s29, v3
	v_add_u32_e32 v122, s28, v26
	v_add_u32_e32 v128, s29, v5
	v_add_u32_e32 v126, s28, v28
	v_add_u32_e32 v132, s29, v7
	v_add_u32_e32 v130, s28, v30
	v_add_u32_e32 v136, s29, v27
	v_add_u32_e32 v134, s28, v32
	v_add_u32_e32 v140, s29, v29
	v_add_u32_e32 v138, s28, v34
	v_add_u32_e32 v144, s29, v31
	v_add_u32_e32 v142, s28, v36
	v_add_u32_e32 v148, s29, v33
	v_add_u32_e32 v146, s28, v38
	s_cmp_lg_u32 s16, 0
	v_mad_u64_u32 v[118:119], s[28:29], v118, s83, v[6:7]
	v_mad_u64_u32 v[120:121], s[28:29], v120, s83, v[6:7]
	v_mad_u64_u32 v[122:123], s[28:29], v122, s83, v[6:7]
	v_mad_u64_u32 v[124:125], s[28:29], v124, s83, v[6:7]
	v_mad_u64_u32 v[126:127], s[28:29], v126, s83, v[6:7]
	v_mad_u64_u32 v[128:129], s[28:29], v128, s83, v[6:7]
	v_mad_u64_u32 v[130:131], s[28:29], v130, s83, v[6:7]
	v_mad_u64_u32 v[132:133], s[28:29], v132, s83, v[6:7]
	v_mad_u64_u32 v[134:135], s[28:29], v134, s83, v[6:7]
	v_mad_u64_u32 v[136:137], s[28:29], v136, s83, v[6:7]
	v_mad_u64_u32 v[138:139], s[28:29], v138, s83, v[6:7]
	v_mad_u64_u32 v[140:141], s[28:29], v140, s83, v[6:7]
	v_mad_u64_u32 v[142:143], s[28:29], v142, s83, v[6:7]
	v_mad_u64_u32 v[144:145], s[28:29], v144, s83, v[6:7]
	v_mad_u64_u32 v[146:147], s[28:29], v146, s83, v[6:7]
	v_mad_u64_u32 v[148:149], s[28:29], v148, s83, v[6:7]
	s_waitcnt vmcnt(16)
	ds_write_b32 v62, v61
	ds_write_b32 v64, v94
	ds_write_b32 v66, v95
	ds_write_b32 v68, v96
	ds_write_b32 v70, v97
	ds_write_b32 v72, v98
	ds_write_b32 v74, v99
	ds_write_b32 v76, v100
	ds_write_b32 v78, v101
	ds_write_b32 v80, v102
	ds_write_b32 v82, v103
	ds_write_b32 v84, v104
	ds_write_b32 v86, v105
	ds_write_b32 v88, v106
	ds_write_b32 v90, v107
	ds_write_b32 v92, v108
	s_waitcnt vmcnt(0)
	ds_write_b32 v118, v117
	ds_write_b32 v120, v150
	ds_write_b32 v122, v151
	ds_write_b32 v124, v152
	ds_write_b32 v126, v153
	ds_write_b32 v128, v154
	ds_write_b32 v130, v155
	ds_write_b32 v132, v156
	ds_write_b32 v134, v157
	ds_write_b32 v136, v158
	ds_write_b32 v138, v159
	ds_write_b32 v140, v160
	ds_write_b32 v142, v161
	ds_write_b32 v144, v162
	ds_write_b32 v146, v163
	ds_write_b32 v148, v164
	s_waitcnt lgkmcnt(0)
	ds_read2_b32 v[44:45], v57 offset0:33 offset1:41
	ds_read2_b32 v[46:47], v57 offset1:8
	ds_read2_b32 v[48:49], v57 offset0:66 offset1:74
	ds_read2_b32 v[50:51], v57 offset0:99 offset1:107
	ds_read2_b32 v[62:63], v57 offset0:132 offset1:140
	ds_read2_b32 v[64:65], v57 offset0:165 offset1:173
	ds_read2_b32 v[66:67], v57 offset0:198 offset1:206
	ds_read2_b32 v[68:69], v57 offset0:231 offset1:239
	s_and_b32 s2, 0xffff, s12
	v_add_u32_e32 v72, s2, v55
	s_lshl_b32 s16, s3, 1
	v_ashrrev_i32_e32 v73, 31, v72
	v_lshl_add_u64 v[70:71], v[14:15], 0, s[16:17]
	v_lshlrev_b64 v[72:73], 11, v[72:73]
	s_waitcnt lgkmcnt(6)
	v_cvt_pk_f16_f32 v40, v46, v44
	s_waitcnt lgkmcnt(4)
	v_cvt_pk_f16_f32 v41, v48, v50
	s_waitcnt lgkmcnt(2)
	v_cvt_pk_f16_f32 v42, v62, v64
	s_waitcnt lgkmcnt(0)
	v_cvt_pk_f16_f32 v43, v66, v68
	v_lshl_add_u64 v[72:73], v[70:71], 0, v[72:73]
	v_add_u32_e32 v44, s2, v58
	global_store_dwordx4 v[72:73], v[40:43], off
	s_nop 1
	v_cvt_pk_f16_f32 v40, v47, v45
	v_ashrrev_i32_e32 v45, 31, v44
	v_cvt_pk_f16_f32 v41, v49, v51
	v_cvt_pk_f16_f32 v42, v63, v65
	v_cvt_pk_f16_f32 v43, v67, v69
	v_lshlrev_b64 v[44:45], 11, v[44:45]
	ds_read2_b32 v[46:47], v57 offset0:49 offset1:57
	ds_read2_b32 v[48:49], v57 offset0:16 offset1:24
	ds_read2_b32 v[50:51], v57 offset0:82 offset1:90
	ds_read2_b32 v[62:63], v57 offset0:115 offset1:123
	ds_read2_b32 v[64:65], v57 offset0:148 offset1:156
	ds_read2_b32 v[66:67], v57 offset0:181 offset1:189
	ds_read2_b32 v[68:69], v57 offset0:214 offset1:222
	ds_read2_b32 v[72:73], v57 offset0:247 offset1:255
	v_lshl_add_u64 v[44:45], v[70:71], 0, v[44:45]
	global_store_dwordx4 v[44:45], v[40:43], off
	v_add_u32_e32 v44, s2, v59
	v_ashrrev_i32_e32 v45, 31, v44
	v_lshlrev_b64 v[44:45], 11, v[44:45]
	s_waitcnt lgkmcnt(6)
	v_cvt_pk_f16_f32 v40, v48, v46
	s_waitcnt lgkmcnt(4)
	v_cvt_pk_f16_f32 v41, v50, v62
	s_waitcnt lgkmcnt(2)
	v_cvt_pk_f16_f32 v42, v64, v66
	s_waitcnt lgkmcnt(0)
	v_cvt_pk_f16_f32 v43, v68, v72
	v_lshl_add_u64 v[44:45], v[70:71], 0, v[44:45]
	global_store_dwordx4 v[44:45], v[40:43], off
	v_add_u32_e32 v44, s2, v60
	v_ashrrev_i32_e32 v45, 31, v44
	v_lshlrev_b64 v[44:45], 11, v[44:45]
	v_cvt_pk_f16_f32 v40, v49, v47
	v_cvt_pk_f16_f32 v41, v51, v63
	v_cvt_pk_f16_f32 v42, v65, v67
	v_cvt_pk_f16_f32 v43, v69, v73
	v_lshl_add_u64 v[44:45], v[70:71], 0, v[44:45]
	global_store_dwordx4 v[44:45], v[40:43], off
	s_waitcnt lgkmcnt(0)

; template <int MODE> __device__ __forceinline__ void transpose_item(const float* __restrict__ W, int N, bf16_t* __restrict__ WT, int ldk, LAS float* scr, int item, int lane) {
;     const int nblk = N / 32, kb = item / nblk, nb = item % nblk, k0 = 64 * kb, n0 = 32 * nb;
; #pragma unroll 8
;     for (int i = 0; i < 32; ++i) { const int kk = 2 * i + (lane >> 5); scr[kk * 33 + (lane & 31)] = W[(size_t)(k0 + kk) * N + n0 + (lane & 31)]; }
.LBB0_1054:
	s_lshl_b32 s34, s13, 1
	s_lshl_b32 s35, s12, 1
	v_add_u32_e32 v62, s34, v42
	v_add_u32_e32 v61, s35, v35
	v_add_u32_e32 v68, s35, v37
	v_add_u32_e32 v66, s34, v44
	v_add_u32_e32 v72, s35, v39
	v_add_u32_e32 v70, s34, v46
	v_add_u32_e32 v76, s35, v43
	v_add_u32_e32 v74, s34, v48
	v_add_u32_e32 v80, s35, v45
	v_add_u32_e32 v78, s34, v50
	v_add_u32_e32 v84, s35, v47
	v_add_u32_e32 v82, s34, v52
	v_add_u32_e32 v88, s35, v49
	v_add_u32_e32 v86, s34, v54
	v_add_u32_e32 v92, s35, v51
	v_add_u32_e32 v90, s34, v56
	v_mad_i64_i32 v[62:63], s[28:29], v62, s86, v[40:41]
	v_mad_i64_i32 v[64:65], s[28:29], v61, s86, v[40:41]
	v_mad_i64_i32 v[66:67], s[28:29], v66, s86, v[40:41]
	v_mad_i64_i32 v[68:69], s[28:29], v68, s86, v[40:41]
	v_mad_i64_i32 v[70:71], s[28:29], v70, s86, v[40:41]
	v_mad_i64_i32 v[72:73], s[28:29], v72, s86, v[40:41]
	v_mad_i64_i32 v[74:75], s[28:29], v74, s86, v[40:41]
	v_mad_i64_i32 v[76:77], s[28:29], v76, s86, v[40:41]
	v_mad_i64_i32 v[78:79], s[28:29], v78, s86, v[40:41]
	v_mad_i64_i32 v[80:81], s[28:29], v80, s86, v[40:41]
	v_mad_i64_i32 v[82:83], s[28:29], v82, s86, v[40:41]
	v_mad_i64_i32 v[84:85], s[28:29], v84, s86, v[40:41]
	v_mad_i64_i32 v[86:87], s[28:29], v86, s86, v[40:41]
	v_mad_i64_i32 v[88:89], s[28:29], v88, s86, v[40:41]
	v_mad_i64_i32 v[90:91], s[28:29], v90, s86, v[40:41]
	v_mad_i64_i32 v[92:93], s[28:29], v92, s86, v[40:41]
	global_load_dword v61, v[62:63], off
	global_load_dword v94, v[64:65], off
	global_load_dword v95, v[66:67], off
	global_load_dword v96, v[68:69], off
	global_load_dword v97, v[70:71], off
	global_load_dword v98, v[72:73], off
	global_load_dword v99, v[74:75], off
	global_load_dword v100, v[76:77], off
	global_load_dword v101, v[78:79], off
	global_load_dword v102, v[80:81], off
	global_load_dword v103, v[82:83], off
	global_load_dword v104, v[84:85], off
	global_load_dword v105, v[86:87], off
	global_load_dword v106, v[88:89], off
	global_load_dword v107, v[90:91], off
	global_load_dword v108, v[92:93], off
	s_add_i32 s13, s13, 16
	s_add_i32 s12, s12, 16
	s_add_i32 s16, s16, -16
	v_add_u32_e32 v62, s34, v2
	v_add_u32_e32 v64, s35, v1
	v_add_u32_e32 v68, s35, v3
	v_add_u32_e32 v66, s34, v26
	v_add_u32_e32 v72, s35, v5
	v_add_u32_e32 v70, s34, v28
	v_add_u32_e32 v76, s35, v7
	v_add_u32_e32 v74, s34, v30
	v_add_u32_e32 v80, s35, v27
	v_add_u32_e32 v78, s34, v32
	v_add_u32_e32 v84, s35, v29
	v_add_u32_e32 v82, s34, v34
	v_add_u32_e32 v88, s35, v31
	v_add_u32_e32 v86, s34, v36
	v_add_u32_e32 v92, s35, v33
	v_add_u32_e32 v90, s34, v38
	s_cmp_lg_u32 s16, 0
	v_mad_u64_u32 v[62:63], s[28:29], v62, s83, v[6:7]
	v_mad_u64_u32 v[64:65], s[28:29], v64, s83, v[6:7]
	v_mad_u64_u32 v[66:67], s[28:29], v66, s83, v[6:7]
	v_mad_u64_u32 v[68:69], s[28:29], v68, s83, v[6:7]
	v_mad_u64_u32 v[70:71], s[28:29], v70, s83, v[6:7]
	v_mad_u64_u32 v[72:73], s[28:29], v72, s83, v[6:7]
	v_mad_u64_u32 v[74:75], s[28:29], v74, s83, v[6:7]
	v_mad_u64_u32 v[76:77], s[28:29], v76, s83, v[6:7]
	v_mad_u64_u32 v[78:79], s[28:29], v78, s83, v[6:7]
	v_mad_u64_u32 v[80:81], s[28:29], v80, s83, v[6:7]
	v_mad_u64_u32 v[82:83], s[28:29], v82, s83, v[6:7]
	v_mad_u64_u32 v[84:85], s[28:29], v84, s83, v[6:7]
	v_mad_u64_u32 v[86:87], s[28:29], v86, s83, v[6:7]
	v_mad_u64_u32 v[88:89], s[28:29], v88, s83, v[6:7]
	v_mad_u64_u32 v[90:91], s[28:29], v90, s83, v[6:7]
	v_mad_u64_u32 v[92:93], s[28:29], v92, s83, v[6:7]
	s_lshl_b32 s34, s13, 1
	s_lshl_b32 s35, s12, 1
	v_add_u32_e32 v118, s34, v42
	v_add_u32_e32 v117, s35, v35
	v_add_u32_e32 v124, s35, v37
	v_add_u32_e32 v122, s34, v44
	v_add_u32_e32 v128, s35, v39
	v_add_u32_e32 v126, s34, v46
	v_add_u32_e32 v132, s35, v43
	v_add_u32_e32 v130, s34, v48
	v_add_u32_e32 v136, s35, v45
	v_add_u32_e32 v134, s34, v50
	v_add_u32_e32 v140, s35, v47
	v_add_u32_e32 v138, s34, v52
	v_add_u32_e32 v144, s35, v49
	v_add_u32_e32 v142, s34, v54
	v_add_u32_e32 v148, s35, v51
	v_add_u32_e32 v146, s34, v56
	v_mad_i64_i32 v[118:119], s[28:29], v118, s86, v[40:41]
	v_mad_i64_i32 v[120:121], s[28:29], v117, s86, v[40:41]
	v_mad_i64_i32 v[122:123], s[28:29], v122, s86, v[40:41]
	v_mad_i64_i32 v[124:125], s[28:29], v124, s86, v[40:41]
	v_mad_i64_i32 v[126:127], s[28:29], v126, s86, v[40:41]
	v_mad_i64_i32 v[128:129], s[28:29], v128, s86, v[40:41]
	v_mad_i64_i32 v[130:131], s[28:29], v130, s86, v[40:41]
	v_mad_i64_i32 v[132:133], s[28:29], v132, s86, v[40:41]
	v_mad_i64_i32 v[134:135], s[28:29], v134, s86, v[40:41]
	v_mad_i64_i32 v[136:137], s[28:29], v136, s86, v[40:41]
	v_mad_i64_i32 v[138:139], s[28:29], v138, s86, v[40:41]
	v_mad_i64_i32 v[140:141], s[28:29], v140, s86, v[40:41]
	v_mad_i64_i32 v[142:143], s[28:29], v142, s86, v[40:41]
	v_mad_i64_i32 v[144:145], s[28:29], v144, s86, v[40:41]
	v_mad_i64_i32 v[146:147], s[28:29], v146, s86, v[40:41]
	v_mad_i64_i32 v[148:149], s[28:29], v148, s86, v[40:41]
	global_load_dword v117, v[118:119], off
	global_load_dword v150, v[120:121], off
	global_load_dword v151, v[122:123], off
	global_load_dword v152, v[124:125], off
	global_load_dword v153, v[126:127], off
	global_load_dword v154, v[128:129], off
	global_load_dword v155, v[130:131], off
	global_load_dword v156, v[132:133], off
	global_load_dword v157, v[134:135], off
	global_load_dword v158, v[136:137], off
	global_load_dword v159, v[138:139], off
	global_load_dword v160, v[140:141], off
	global_load_dword v161, v[142:143], off
	global_load_dword v162, v[144:145], off
	global_load_dword v163, v[146:147], off
	global_load_dword v164, v[148:149], off
	s_add_i32 s13, s13, 16
	s_add_i32 s12, s12, 16
	s_add_i32 s16, s16, -16
	v_add_u32_e32 v118, s34, v2
	v_add_u32_e32 v120, s35, v1
	v_add_u32_e32 v124, s35, v3
	v_add_u32_e32 v122, s34, v26
	v_add_u32_e32 v128, s35, v5
	v_add_u32_e32 v126, s34, v28
	v_add_u32_e32 v132, s35, v7
	v_add_u32_e32 v130, s34, v30
	v_add_u32_e32 v136, s35, v27
	v_add_u32_e32 v134, s34, v32
	v_add_u32_e32 v140, s35, v29
	v_add_u32_e32 v138, s34, v34
	v_add_u32_e32 v144, s35, v31
	v_add_u32_e32 v142, s34, v36
	v_add_u32_e32 v148, s35, v33
	v_add_u32_e32 v146, s34, v38
	s_cmp_lg_u32 s16, 0
	v_mad_u64_u32 v[118:119], s[28:29], v118, s83, v[6:7]
	v_mad_u64_u32 v[120:121], s[28:29], v120, s83, v[6:7]
	v_mad_u64_u32 v[122:123], s[28:29], v122, s83, v[6:7]
	v_mad_u64_u32 v[124:125], s[28:29], v124, s83, v[6:7]
	v_mad_u64_u32 v[126:127], s[28:29], v126, s83, v[6:7]
	v_mad_u64_u32 v[128:129], s[28:29], v128, s83, v[6:7]
	v_mad_u64_u32 v[130:131], s[28:29], v130, s83, v[6:7]
	v_mad_u64_u32 v[132:133], s[28:29], v132, s83, v[6:7]
	v_mad_u64_u32 v[134:135], s[28:29], v134, s83, v[6:7]
	v_mad_u64_u32 v[136:137], s[28:29], v136, s83, v[6:7]
	v_mad_u64_u32 v[138:139], s[28:29], v138, s83, v[6:7]
	v_mad_u64_u32 v[140:141], s[28:29], v140, s83, v[6:7]
	v_mad_u64_u32 v[142:143], s[28:29], v142, s83, v[6:7]
	v_mad_u64_u32 v[144:145], s[28:29], v144, s83, v[6:7]
	v_mad_u64_u32 v[146:147], s[28:29], v146, s83, v[6:7]
	v_mad_u64_u32 v[148:149], s[28:29], v148, s83, v[6:7]
	s_waitcnt vmcnt(16)
; #define LAS __attribute__((address_space(3)))
; __device__ __forceinline__ unsigned pk2(float lo, float hi) { return pg8::cvt_pk_bf16(lo, hi); }
; #define LDS_WAIT() asm volatile("s_waitcnt lgkmcnt(0)" ::: "memory")
; template <int MODE> __device__ __forceinline__ void transpose_item(const float* __restrict__ W, int N, bf16_t* __restrict__ WT, int ldk, LAS float* scr, int item, int lane) {
;     ...
;     for (int i = 0; i < 32; ++i) { const int kk = 2 * i + (lane >> 5); scr[kk * 33 + (lane & 31)] = W[(size_t)(k0 + kk) * N + n0 + (lane & 31)]; }
;     LDS_WAIT();
;     const int c = lane & 7, r0 = dest_row<MODE>(n0);
; #pragma unroll
;     for (int j = 0; j < 4; ++j) { const int n = (lane >> 3) + 8 * j; const LAS float* s = scr + (8 * c) * 33 + n;
;         u32x4 o; o.x = pk2(s[0 * 33], s[1 * 33]); o.y = pk2(s[2 * 33], s[3 * 33]); o.z = pk2(s[4 * 33], s[5 * 33]); o.w = pk2(s[6 * 33], s[7 * 33]);
;         *(u32x4*)(WT + (size_t)(r0 + n) * ldk + k0 + 8 * c) = o; }
;     LDS_WAIT();
	ds_write_b32 v62, v61
	ds_write_b32 v64, v94
	ds_write_b32 v66, v95
	ds_write_b32 v68, v96
	ds_write_b32 v70, v97
	ds_write_b32 v72, v98
	ds_write_b32 v74, v99
	ds_write_b32 v76, v100
	ds_write_b32 v78, v101
	ds_write_b32 v80, v102
	ds_write_b32 v82, v103
	ds_write_b32 v84, v104
	ds_write_b32 v86, v105
	ds_write_b32 v88, v106
	ds_write_b32 v90, v107
	ds_write_b32 v92, v108
	s_waitcnt vmcnt(0)
	ds_write_b32 v118, v117
	ds_write_b32 v120, v150
	ds_write_b32 v122, v151
	ds_write_b32 v124, v152
	ds_write_b32 v126, v153
	ds_write_b32 v128, v154
	ds_write_b32 v130, v155
	ds_write_b32 v132, v156
	ds_write_b32 v134, v157
	ds_write_b32 v136, v158
	ds_write_b32 v138, v159
	ds_write_b32 v140, v160
	ds_write_b32 v142, v161
	ds_write_b32 v144, v162
	ds_write_b32 v146, v163
	ds_write_b32 v148, v164
	s_waitcnt lgkmcnt(0)
	ds_read2_b32 v[44:45], v57 offset0:33 offset1:41
	ds_read2_b32 v[46:47], v57 offset1:8
	ds_read2_b32 v[48:49], v57 offset0:66 offset1:74
	ds_read2_b32 v[50:51], v57 offset0:99 offset1:107
	ds_read2_b32 v[62:63], v57 offset0:132 offset1:140
	ds_read2_b32 v[64:65], v57 offset0:165 offset1:173
	ds_read2_b32 v[66:67], v57 offset0:198 offset1:206
	ds_read2_b32 v[68:69], v57 offset0:231 offset1:239
	s_and_b32 s3, 0xffff, s3
	v_add_u32_e32 v72, s3, v55
	s_lshl_b32 s16, s2, 1
	v_ashrrev_i32_e32 v73, 31, v72
	v_lshl_add_u64 v[70:71], v[16:17], 0, s[16:17]
	v_lshlrev_b64 v[72:73], 11, v[72:73]
	s_waitcnt lgkmcnt(6)
	v_cvt_pk_f16_f32 v40, v46, v44
	s_waitcnt lgkmcnt(4)
	v_cvt_pk_f16_f32 v41, v48, v50
	s_waitcnt lgkmcnt(2)
	v_cvt_pk_f16_f32 v42, v62, v64
	s_waitcnt lgkmcnt(0)
	v_cvt_pk_f16_f32 v43, v66, v68
	v_lshl_add_u64 v[72:73], v[70:71], 0, v[72:73]
	v_add_u32_e32 v44, s3, v58
	global_store_dwordx4 v[72:73], v[40:43], off
	s_nop 1
	v_cvt_pk_f16_f32 v40, v47, v45
	v_ashrrev_i32_e32 v45, 31, v44
	v_cvt_pk_f16_f32 v41, v49, v51
	v_cvt_pk_f16_f32 v42, v63, v65
	v_cvt_pk_f16_f32 v43, v67, v69
	v_lshlrev_b64 v[44:45], 11, v[44:45]
	ds_read2_b32 v[46:47], v57 offset0:49 offset1:57
	ds_read2_b32 v[48:49], v57 offset0:16 offset1:24
	ds_read2_b32 v[50:51], v57 offset0:82 offset1:90
	ds_read2_b32 v[62:63], v57 offset0:115 offset1:123
	ds_read2_b32 v[64:65], v57 offset0:148 offset1:156
	ds_read2_b32 v[66:67], v57 offset0:181 offset1:189
	ds_read2_b32 v[68:69], v57 offset0:214 offset1:222
	ds_read2_b32 v[72:73], v57 offset0:247 offset1:255
	v_lshl_add_u64 v[44:45], v[70:71], 0, v[44:45]
	global_store_dwordx4 v[44:45], v[40:43], off
	v_add_u32_e32 v44, s3, v59
	v_ashrrev_i32_e32 v45, 31, v44
	v_lshlrev_b64 v[44:45], 11, v[44:45]
	s_waitcnt lgkmcnt(6)
	v_cvt_pk_f16_f32 v40, v48, v46
	s_waitcnt lgkmcnt(4)
	v_cvt_pk_f16_f32 v41, v50, v62
	s_waitcnt lgkmcnt(2)
	v_cvt_pk_f16_f32 v42, v64, v66
	s_waitcnt lgkmcnt(0)
	v_cvt_pk_f16_f32 v43, v68, v72
	v_lshl_add_u64 v[44:45], v[70:71], 0, v[44:45]
	global_store_dwordx4 v[44:45], v[40:43], off
	v_add_u32_e32 v44, s3, v60
	v_ashrrev_i32_e32 v45, 31, v44
	v_lshlrev_b64 v[44:45], 11, v[44:45]
	v_cvt_pk_f16_f32 v40, v49, v47
	v_cvt_pk_f16_f32 v41, v51, v63
	v_cvt_pk_f16_f32 v42, v65, v67
	v_cvt_pk_f16_f32 v43, v69, v73
	v_lshl_add_u64 v[44:45], v[70:71], 0, v[44:45]
	global_store_dwordx4 v[44:45], v[40:43], off
	s_waitcnt lgkmcnt(0)

; template <int MODE> __device__ __forceinline__ void transpose_item(const float* __restrict__ W, int N, bf16_t* __restrict__ WT, int ldk, LAS float* scr, int item, int lane) {
;     const int nblk = N / 32, kb = item / nblk, nb = item % nblk, k0 = 64 * kb, n0 = 32 * nb;
; #pragma unroll 8
;     for (int i = 0; i < 32; ++i) { const int kk = 2 * i + (lane >> 5); scr[kk * 33 + (lane & 31)] = W[(size_t)(k0 + kk) * N + n0 + (lane & 31)]; }
.LBB0_1059:
	s_lshl_b32 s28, s13, 1
	s_lshl_b32 s29, s2, 1
	v_add_u32_e32 v64, s28, v42
	v_add_u32_e32 v62, s29, v35
	v_add_u32_e32 v66, s29, v37
	v_add_u32_e32 v68, s28, v44
	v_add_u32_e32 v70, s29, v39
	v_add_u32_e32 v72, s28, v46
	v_add_u32_e32 v74, s29, v43
	v_add_u32_e32 v76, s28, v48
	v_add_u32_e32 v78, s29, v45
	v_add_u32_e32 v80, s28, v50
	v_add_u32_e32 v82, s29, v47
	v_add_u32_e32 v84, s28, v52
	v_add_u32_e32 v86, s29, v49
	v_add_u32_e32 v88, s28, v54
	v_add_u32_e32 v90, s29, v51
	v_add_u32_e32 v92, s28, v56
	v_ashrrev_i32_e32 v65, 31, v64
	v_ashrrev_i32_e32 v63, 31, v62
	v_ashrrev_i32_e32 v69, 31, v68
	v_ashrrev_i32_e32 v67, 31, v66
	v_ashrrev_i32_e32 v73, 31, v72
	v_ashrrev_i32_e32 v71, 31, v70
	v_ashrrev_i32_e32 v77, 31, v76
	v_ashrrev_i32_e32 v75, 31, v74
	v_ashrrev_i32_e32 v81, 31, v80
	v_ashrrev_i32_e32 v79, 31, v78
	v_ashrrev_i32_e32 v85, 31, v84
	v_ashrrev_i32_e32 v83, 31, v82
	v_ashrrev_i32_e32 v89, 31, v88
	v_ashrrev_i32_e32 v87, 31, v86
	v_ashrrev_i32_e32 v93, 31, v92
	v_ashrrev_i32_e32 v91, 31, v90
	v_lshlrev_b64 v[64:65], 12, v[64:65]
	v_lshlrev_b64 v[62:63], 12, v[62:63]
	v_lshlrev_b64 v[66:67], 12, v[66:67]
	v_lshlrev_b64 v[68:69], 12, v[68:69]
	v_lshlrev_b64 v[70:71], 12, v[70:71]
	v_lshlrev_b64 v[72:73], 12, v[72:73]
	v_lshlrev_b64 v[74:75], 12, v[74:75]
	v_lshlrev_b64 v[76:77], 12, v[76:77]
	v_lshlrev_b64 v[78:79], 12, v[78:79]
	v_lshlrev_b64 v[80:81], 12, v[80:81]
	v_lshlrev_b64 v[82:83], 12, v[82:83]
	v_lshlrev_b64 v[84:85], 12, v[84:85]
	v_lshlrev_b64 v[86:87], 12, v[86:87]
	v_lshlrev_b64 v[88:89], 12, v[88:89]
	v_lshlrev_b64 v[90:91], 12, v[90:91]
	v_lshlrev_b64 v[92:93], 12, v[92:93]
	v_lshl_add_u64 v[64:65], v[40:41], 0, v[64:65]
	v_lshl_add_u64 v[62:63], v[40:41], 0, v[62:63]
	v_lshl_add_u64 v[68:69], v[40:41], 0, v[68:69]
	v_lshl_add_u64 v[66:67], v[40:41], 0, v[66:67]
	v_lshl_add_u64 v[72:73], v[40:41], 0, v[72:73]
	v_lshl_add_u64 v[70:71], v[40:41], 0, v[70:71]
	v_lshl_add_u64 v[76:77], v[40:41], 0, v[76:77]
	v_lshl_add_u64 v[74:75], v[40:41], 0, v[74:75]
	v_lshl_add_u64 v[80:81], v[40:41], 0, v[80:81]
	v_lshl_add_u64 v[78:79], v[40:41], 0, v[78:79]
	v_lshl_add_u64 v[84:85], v[40:41], 0, v[84:85]
	v_lshl_add_u64 v[82:83], v[40:41], 0, v[82:83]
	v_lshl_add_u64 v[88:89], v[40:41], 0, v[88:89]
	v_lshl_add_u64 v[86:87], v[40:41], 0, v[86:87]
	v_lshl_add_u64 v[92:93], v[40:41], 0, v[92:93]
	v_lshl_add_u64 v[90:91], v[40:41], 0, v[90:91]
	global_load_dword v61, v[64:65], off
	global_load_dword v94, v[62:63], off
	global_load_dword v95, v[68:69], off
	global_load_dword v96, v[66:67], off
	global_load_dword v97, v[72:73], off
	global_load_dword v98, v[70:71], off
	global_load_dword v99, v[76:77], off
	global_load_dword v100, v[74:75], off
	global_load_dword v101, v[80:81], off
	global_load_dword v102, v[78:79], off
	global_load_dword v103, v[84:85], off
	global_load_dword v104, v[82:83], off
	global_load_dword v105, v[88:89], off
	global_load_dword v106, v[86:87], off
	global_load_dword v107, v[92:93], off
	global_load_dword v108, v[90:91], off
	s_add_i32 s13, s13, 16
	s_add_i32 s2, s2, 16
	s_add_i32 s16, s16, -16
	v_add_u32_e32 v62, s28, v2
	v_add_u32_e32 v64, s29, v1
	v_add_u32_e32 v68, s29, v3
	v_add_u32_e32 v66, s28, v26
	v_add_u32_e32 v72, s29, v5
	v_add_u32_e32 v70, s28, v28
	v_add_u32_e32 v76, s29, v7
	v_add_u32_e32 v74, s28, v30
	v_add_u32_e32 v80, s29, v27
	v_add_u32_e32 v78, s28, v32
	v_add_u32_e32 v84, s29, v29
	v_add_u32_e32 v82, s28, v34
	v_add_u32_e32 v88, s29, v31
	v_add_u32_e32 v86, s28, v36
	v_add_u32_e32 v92, s29, v33
	v_add_u32_e32 v90, s28, v38
	s_cmp_lg_u32 s16, 0
	v_mad_u64_u32 v[62:63], s[28:29], v62, s83, v[6:7]
	v_mad_u64_u32 v[64:65], s[28:29], v64, s83, v[6:7]
	v_mad_u64_u32 v[66:67], s[28:29], v66, s83, v[6:7]
	v_mad_u64_u32 v[68:69], s[28:29], v68, s83, v[6:7]
	v_mad_u64_u32 v[70:71], s[28:29], v70, s83, v[6:7]
	v_mad_u64_u32 v[72:73], s[28:29], v72, s83, v[6:7]
	v_mad_u64_u32 v[74:75], s[28:29], v74, s83, v[6:7]
	v_mad_u64_u32 v[76:77], s[28:29], v76, s83, v[6:7]
	v_mad_u64_u32 v[78:79], s[28:29], v78, s83, v[6:7]
	v_mad_u64_u32 v[80:81], s[28:29], v80, s83, v[6:7]
	v_mad_u64_u32 v[82:83], s[28:29], v82, s83, v[6:7]
	v_mad_u64_u32 v[84:85], s[28:29], v84, s83, v[6:7]
	v_mad_u64_u32 v[86:87], s[28:29], v86, s83, v[6:7]
	v_mad_u64_u32 v[88:89], s[28:29], v88, s83, v[6:7]
	v_mad_u64_u32 v[90:91], s[28:29], v90, s83, v[6:7]
	v_mad_u64_u32 v[92:93], s[28:29], v92, s83, v[6:7]
	s_lshl_b32 s28, s13, 1
	s_lshl_b32 s29, s2, 1
	v_add_u32_e32 v120, s28, v42
	v_add_u32_e32 v118, s29, v35
	v_add_u32_e32 v122, s29, v37
	v_add_u32_e32 v124, s28, v44
	v_add_u32_e32 v126, s29, v39
	v_add_u32_e32 v128, s28, v46
	v_add_u32_e32 v130, s29, v43
	v_add_u32_e32 v132, s28, v48
	v_add_u32_e32 v134, s29, v45
	v_add_u32_e32 v136, s28, v50
	v_add_u32_e32 v138, s29, v47
	v_add_u32_e32 v140, s28, v52
	v_add_u32_e32 v142, s29, v49
	v_add_u32_e32 v144, s28, v54
	v_add_u32_e32 v146, s29, v51
	v_add_u32_e32 v148, s28, v56
	v_ashrrev_i32_e32 v121, 31, v120
	v_ashrrev_i32_e32 v119, 31, v118
	v_ashrrev_i32_e32 v125, 31, v124
	v_ashrrev_i32_e32 v123, 31, v122
	v_ashrrev_i32_e32 v129, 31, v128
	v_ashrrev_i32_e32 v127, 31, v126
	v_ashrrev_i32_e32 v133, 31, v132
	v_ashrrev_i32_e32 v131, 31, v130
	v_ashrrev_i32_e32 v137, 31, v136
	v_ashrrev_i32_e32 v135, 31, v134
	v_ashrrev_i32_e32 v141, 31, v140
	v_ashrrev_i32_e32 v139, 31, v138
	v_ashrrev_i32_e32 v145, 31, v144
	v_ashrrev_i32_e32 v143, 31, v142
	v_ashrrev_i32_e32 v149, 31, v148
	v_ashrrev_i32_e32 v147, 31, v146
	v_lshlrev_b64 v[120:121], 12, v[120:121]
	v_lshlrev_b64 v[118:119], 12, v[118:119]
	v_lshlrev_b64 v[122:123], 12, v[122:123]
	v_lshlrev_b64 v[124:125], 12, v[124:125]
; #define LAS __attribute__((address_space(3)))
; __device__ __forceinline__ unsigned pk2(float lo, float hi) { return pg8::cvt_pk_bf16(lo, hi); }
; #define LDS_WAIT() asm volatile("s_waitcnt lgkmcnt(0)" ::: "memory")
; template <int MODE> __device__ __forceinline__ void transpose_item(const float* __restrict__ W, int N, bf16_t* __restrict__ WT, int ldk, LAS float* scr, int item, int lane) {
;     ...
;     for (int i = 0; i < 32; ++i) { const int kk = 2 * i + (lane >> 5); scr[kk * 33 + (lane & 31)] = W[(size_t)(k0 + kk) * N + n0 + (lane & 31)]; }
;     LDS_WAIT();
;     const int c = lane & 7, r0 = dest_row<MODE>(n0);
; #pragma unroll
;     for (int j = 0; j < 4; ++j) { const int n = (lane >> 3) + 8 * j; const LAS float* s = scr + (8 * c) * 33 + n;
;         u32x4 o; o.x = pk2(s[0 * 33], s[1 * 33]); o.y = pk2(s[2 * 33], s[3 * 33]); o.z = pk2(s[4 * 33], s[5 * 33]); o.w = pk2(s[6 * 33], s[7 * 33]);
;         *(u32x4*)(WT + (size_t)(r0 + n) * ldk + k0 + 8 * c) = o; }
;     LDS_WAIT();
	v_lshlrev_b64 v[126:127], 12, v[126:127]
	v_lshlrev_b64 v[128:129], 12, v[128:129]
	v_lshlrev_b64 v[130:131], 12, v[130:131]
	v_lshlrev_b64 v[132:133], 12, v[132:133]
	v_lshlrev_b64 v[134:135], 12, v[134:135]
	v_lshlrev_b64 v[136:137], 12, v[136:137]
	v_lshlrev_b64 v[138:139], 12, v[138:139]
	v_lshlrev_b64 v[140:141], 12, v[140:141]
	v_lshlrev_b64 v[142:143], 12, v[142:143]
	v_lshlrev_b64 v[144:145], 12, v[144:145]
	v_lshlrev_b64 v[146:147], 12, v[146:147]
	v_lshlrev_b64 v[148:149], 12, v[148:149]
	v_lshl_add_u64 v[120:121], v[40:41], 0, v[120:121]
	v_lshl_add_u64 v[118:119], v[40:41], 0, v[118:119]
	v_lshl_add_u64 v[124:125], v[40:41], 0, v[124:125]
	v_lshl_add_u64 v[122:123], v[40:41], 0, v[122:123]
	v_lshl_add_u64 v[128:129], v[40:41], 0, v[128:129]
	v_lshl_add_u64 v[126:127], v[40:41], 0, v[126:127]
	v_lshl_add_u64 v[132:133], v[40:41], 0, v[132:133]
	v_lshl_add_u64 v[130:131], v[40:41], 0, v[130:131]
	v_lshl_add_u64 v[136:137], v[40:41], 0, v[136:137]
	v_lshl_add_u64 v[134:135], v[40:41], 0, v[134:135]
	v_lshl_add_u64 v[140:141], v[40:41], 0, v[140:141]
	v_lshl_add_u64 v[138:139], v[40:41], 0, v[138:139]
	v_lshl_add_u64 v[144:145], v[40:41], 0, v[144:145]
	v_lshl_add_u64 v[142:143], v[40:41], 0, v[142:143]
	v_lshl_add_u64 v[148:149], v[40:41], 0, v[148:149]
	v_lshl_add_u64 v[146:147], v[40:41], 0, v[146:147]
	global_load_dword v117, v[120:121], off
	global_load_dword v150, v[118:119], off
	global_load_dword v151, v[124:125], off
	global_load_dword v152, v[122:123], off
	global_load_dword v153, v[128:129], off
	global_load_dword v154, v[126:127], off
	global_load_dword v155, v[132:133], off
	global_load_dword v156, v[130:131], off
	global_load_dword v157, v[136:137], off
	global_load_dword v158, v[134:135], off
	global_load_dword v159, v[140:141], off
	global_load_dword v160, v[138:139], off
	global_load_dword v161, v[144:145], off
	global_load_dword v162, v[142:143], off
	global_load_dword v163, v[148:149], off
	global_load_dword v164, v[146:147], off
	s_add_i32 s13, s13, 16
	s_add_i32 s2, s2, 16
	s_add_i32 s16, s16, -16
	v_add_u32_e32 v118, s28, v2
	v_add_u32_e32 v120, s29, v1
	v_add_u32_e32 v124, s29, v3
	v_add_u32_e32 v122, s28, v26
	v_add_u32_e32 v128, s29, v5
	v_add_u32_e32 v126, s28, v28
	v_add_u32_e32 v132, s29, v7
	v_add_u32_e32 v130, s28, v30
	v_add_u32_e32 v136, s29, v27
	v_add_u32_e32 v134, s28, v32
	v_add_u32_e32 v140, s29, v29
	v_add_u32_e32 v138, s28, v34
	v_add_u32_e32 v144, s29, v31
	v_add_u32_e32 v142, s28, v36
	v_add_u32_e32 v148, s29, v33
	v_add_u32_e32 v146, s28, v38
	s_cmp_lg_u32 s16, 0
	v_mad_u64_u32 v[118:119], s[28:29], v118, s83, v[6:7]
	v_mad_u64_u32 v[120:121], s[28:29], v120, s83, v[6:7]
	v_mad_u64_u32 v[122:123], s[28:29], v122, s83, v[6:7]
	v_mad_u64_u32 v[124:125], s[28:29], v124, s83, v[6:7]
	v_mad_u64_u32 v[126:127], s[28:29], v126, s83, v[6:7]
	v_mad_u64_u32 v[128:129], s[28:29], v128, s83, v[6:7]
	v_mad_u64_u32 v[130:131], s[28:29], v130, s83, v[6:7]
	v_mad_u64_u32 v[132:133], s[28:29], v132, s83, v[6:7]
	v_mad_u64_u32 v[134:135], s[28:29], v134, s83, v[6:7]
	v_mad_u64_u32 v[136:137], s[28:29], v136, s83, v[6:7]
	v_mad_u64_u32 v[138:139], s[28:29], v138, s83, v[6:7]
	v_mad_u64_u32 v[140:141], s[28:29], v140, s83, v[6:7]
	v_mad_u64_u32 v[142:143], s[28:29], v142, s83, v[6:7]
	v_mad_u64_u32 v[144:145], s[28:29], v144, s83, v[6:7]
	v_mad_u64_u32 v[146:147], s[28:29], v146, s83, v[6:7]
	v_mad_u64_u32 v[148:149], s[28:29], v148, s83, v[6:7]
	s_waitcnt vmcnt(16)
	ds_write_b32 v62, v61
	ds_write_b32 v64, v94
	ds_write_b32 v66, v95
	ds_write_b32 v68, v96
	ds_write_b32 v70, v97
	ds_write_b32 v72, v98
	ds_write_b32 v74, v99
	ds_write_b32 v76, v100
	ds_write_b32 v78, v101
	ds_write_b32 v80, v102
	ds_write_b32 v82, v103
	ds_write_b32 v84, v104
	ds_write_b32 v86, v105
	ds_write_b32 v88, v106
	ds_write_b32 v90, v107
	ds_write_b32 v92, v108
	s_waitcnt vmcnt(0)
	ds_write_b32 v118, v117
	ds_write_b32 v120, v150
	ds_write_b32 v122, v151
	ds_write_b32 v124, v152
	ds_write_b32 v126, v153
	ds_write_b32 v128, v154
	ds_write_b32 v130, v155
	ds_write_b32 v132, v156
	ds_write_b32 v134, v157
	ds_write_b32 v136, v158
	ds_write_b32 v138, v159
	ds_write_b32 v140, v160
	ds_write_b32 v142, v161
	ds_write_b32 v144, v162
	ds_write_b32 v146, v163
	ds_write_b32 v148, v164
	s_waitcnt lgkmcnt(0)
	ds_read2_b32 v[44:45], v57 offset0:33 offset1:41
	ds_read2_b32 v[46:47], v57 offset1:8
	ds_read2_b32 v[48:49], v57 offset0:66 offset1:74
	ds_read2_b32 v[50:51], v57 offset0:99 offset1:107
	ds_read2_b32 v[62:63], v57 offset0:132 offset1:140
	ds_read2_b32 v[64:65], v57 offset0:165 offset1:173
	ds_read2_b32 v[66:67], v57 offset0:198 offset1:206
	ds_read2_b32 v[68:69], v57 offset0:231 offset1:239
	s_and_b32 s12, 0xffff, s12
	s_lshl_b32 s16, s3, 1
	v_lshl_add_u64 v[70:71], v[18:19], 0, s[16:17]
	v_add_u32_e32 v35, s12, v55
	s_waitcnt lgkmcnt(6)
	v_cvt_pk_f16_f32 v40, v46, v44
	s_waitcnt lgkmcnt(4)
	v_cvt_pk_f16_f32 v41, v48, v50
	s_waitcnt lgkmcnt(2)
	v_cvt_pk_f16_f32 v42, v62, v64
	s_waitcnt lgkmcnt(0)
	v_cvt_pk_f16_f32 v43, v66, v68
	v_mad_i64_i32 v[72:73], s[2:3], v35, s81, v[70:71]
	global_store_dwordx4 v[72:73], v[40:43], off
	v_add_u32_e32 v35, s12, v58
	s_nop 0
	v_cvt_pk_f16_f32 v40, v47, v45
	v_cvt_pk_f16_f32 v41, v49, v51
	v_cvt_pk_f16_f32 v42, v63, v65
	v_cvt_pk_f16_f32 v43, v67, v69
	ds_read2_b32 v[46:47], v57 offset0:49 offset1:57
	ds_read2_b32 v[48:49], v57 offset0:16 offset1:24
	ds_read2_b32 v[50:51], v57 offset0:82 offset1:90
	ds_read2_b32 v[62:63], v57 offset0:115 offset1:123
	ds_read2_b32 v[64:65], v57 offset0:148 offset1:156
	ds_read2_b32 v[66:67], v57 offset0:181 offset1:189
	ds_read2_b32 v[68:69], v57 offset0:214 offset1:222
	ds_read2_b32 v[72:73], v57 offset0:247 offset1:255
	v_mad_i64_i32 v[44:45], s[2:3], v35, s81, v[70:71]
	v_add_u32_e32 v35, s12, v59
	global_store_dwordx4 v[44:45], v[40:43], off
	v_mad_i64_i32 v[44:45], s[2:3], v35, s81, v[70:71]
	s_waitcnt lgkmcnt(6)
	v_cvt_pk_f16_f32 v40, v48, v46
	s_waitcnt lgkmcnt(4)
	v_cvt_pk_f16_f32 v41, v50, v62
	s_waitcnt lgkmcnt(2)
	v_cvt_pk_f16_f32 v42, v64, v66
	s_waitcnt lgkmcnt(0)
	v_cvt_pk_f16_f32 v43, v68, v72
	v_add_u32_e32 v35, s12, v60
	global_store_dwordx4 v[44:45], v[40:43], off
	v_mad_i64_i32 v[44:45], s[2:3], v35, s81, v[70:71]
	s_nop 0
	v_cvt_pk_f16_f32 v40, v49, v47
	v_cvt_pk_f16_f32 v41, v51, v63
	v_cvt_pk_f16_f32 v42, v65, v67
	v_cvt_pk_f16_f32 v43, v69, v73
	global_store_dwordx4 v[44:45], v[40:43], off
	s_waitcnt lgkmcnt(0)

; template <int MODE> __device__ __forceinline__ void transpose_item(const float* __restrict__ W, int N, bf16_t* __restrict__ WT, int ldk, LAS float* scr, int item, int lane) {
;     const int nblk = N / 32, kb = item / nblk, nb = item % nblk, k0 = 64 * kb, n0 = 32 * nb;
; #pragma unroll 8
;     for (int i = 0; i < 32; ++i) { const int kk = 2 * i + (lane >> 5); scr[kk * 33 + (lane & 31)] = W[(size_t)(k0 + kk) * N + n0 + (lane & 31)]; }
.LBB0_1064:
	s_lshl_b32 s28, s13, 1
	s_lshl_b32 s29, s2, 1
	v_add_u32_e32 v64, s28, v42
	v_add_u32_e32 v62, s29, v35
	v_add_u32_e32 v66, s29, v37
	v_add_u32_e32 v68, s28, v44
	v_add_u32_e32 v70, s29, v39
	v_add_u32_e32 v72, s28, v46
	v_add_u32_e32 v74, s29, v43
	v_add_u32_e32 v76, s28, v48
	v_add_u32_e32 v78, s29, v45
	v_add_u32_e32 v80, s28, v50
	v_add_u32_e32 v82, s29, v47
	v_add_u32_e32 v84, s28, v52
	v_add_u32_e32 v86, s29, v49
	v_add_u32_e32 v88, s28, v54
	v_add_u32_e32 v90, s29, v51
	v_add_u32_e32 v92, s28, v56
	v_ashrrev_i32_e32 v65, 31, v64
	v_ashrrev_i32_e32 v63, 31, v62
	v_ashrrev_i32_e32 v69, 31, v68
	v_ashrrev_i32_e32 v67, 31, v66
	v_ashrrev_i32_e32 v73, 31, v72
	v_ashrrev_i32_e32 v71, 31, v70
	v_ashrrev_i32_e32 v77, 31, v76
	v_ashrrev_i32_e32 v75, 31, v74
	v_ashrrev_i32_e32 v81, 31, v80
	v_ashrrev_i32_e32 v79, 31, v78
	v_ashrrev_i32_e32 v85, 31, v84
	v_ashrrev_i32_e32 v83, 31, v82
	v_ashrrev_i32_e32 v89, 31, v88
	v_ashrrev_i32_e32 v87, 31, v86
	v_ashrrev_i32_e32 v93, 31, v92
	v_ashrrev_i32_e32 v91, 31, v90
	v_lshlrev_b64 v[64:65], 12, v[64:65]
	v_lshlrev_b64 v[62:63], 12, v[62:63]
	v_lshlrev_b64 v[66:67], 12, v[66:67]
	v_lshlrev_b64 v[68:69], 12, v[68:69]
	v_lshlrev_b64 v[70:71], 12, v[70:71]
	v_lshlrev_b64 v[72:73], 12, v[72:73]
	v_lshlrev_b64 v[74:75], 12, v[74:75]
	v_lshlrev_b64 v[76:77], 12, v[76:77]
	v_lshlrev_b64 v[78:79], 12, v[78:79]
	v_lshlrev_b64 v[80:81], 12, v[80:81]
	v_lshlrev_b64 v[82:83], 12, v[82:83]
	v_lshlrev_b64 v[84:85], 12, v[84:85]
	v_lshlrev_b64 v[86:87], 12, v[86:87]
	v_lshlrev_b64 v[88:89], 12, v[88:89]
	v_lshlrev_b64 v[90:91], 12, v[90:91]
	v_lshlrev_b64 v[92:93], 12, v[92:93]
	v_lshl_add_u64 v[64:65], v[40:41], 0, v[64:65]
	v_lshl_add_u64 v[62:63], v[40:41], 0, v[62:63]
	v_lshl_add_u64 v[68:69], v[40:41], 0, v[68:69]
	v_lshl_add_u64 v[66:67], v[40:41], 0, v[66:67]
	v_lshl_add_u64 v[72:73], v[40:41], 0, v[72:73]
	v_lshl_add_u64 v[70:71], v[40:41], 0, v[70:71]
	v_lshl_add_u64 v[76:77], v[40:41], 0, v[76:77]
	v_lshl_add_u64 v[74:75], v[40:41], 0, v[74:75]
	v_lshl_add_u64 v[80:81], v[40:41], 0, v[80:81]
	v_lshl_add_u64 v[78:79], v[40:41], 0, v[78:79]
	v_lshl_add_u64 v[84:85], v[40:41], 0, v[84:85]
	v_lshl_add_u64 v[82:83], v[40:41], 0, v[82:83]
	v_lshl_add_u64 v[88:89], v[40:41], 0, v[88:89]
	v_lshl_add_u64 v[86:87], v[40:41], 0, v[86:87]
	v_lshl_add_u64 v[92:93], v[40:41], 0, v[92:93]
	v_lshl_add_u64 v[90:91], v[40:41], 0, v[90:91]
	global_load_dword v61, v[64:65], off
	global_load_dword v94, v[62:63], off
	global_load_dword v95, v[68:69], off
	global_load_dword v96, v[66:67], off
	global_load_dword v97, v[72:73], off
	global_load_dword v98, v[70:71], off
	global_load_dword v99, v[76:77], off
	global_load_dword v100, v[74:75], off
	global_load_dword v101, v[80:81], off
	global_load_dword v102, v[78:79], off
	global_load_dword v103, v[84:85], off
	global_load_dword v104, v[82:83], off
	global_load_dword v105, v[88:89], off
	global_load_dword v106, v[86:87], off
	global_load_dword v107, v[92:93], off
	global_load_dword v108, v[90:91], off
	s_add_i32 s13, s13, 16
	s_add_i32 s2, s2, 16
	s_add_i32 s16, s16, -16
	v_add_u32_e32 v62, s28, v2
	v_add_u32_e32 v64, s29, v1
	v_add_u32_e32 v68, s29, v3
	v_add_u32_e32 v66, s28, v26
	v_add_u32_e32 v72, s29, v5
	v_add_u32_e32 v70, s28, v28
	v_add_u32_e32 v76, s29, v7
	v_add_u32_e32 v74, s28, v30
	v_add_u32_e32 v80, s29, v27
	v_add_u32_e32 v78, s28, v32
	v_add_u32_e32 v84, s29, v29
	v_add_u32_e32 v82, s28, v34
	v_add_u32_e32 v88, s29, v31
	v_add_u32_e32 v86, s28, v36
	v_add_u32_e32 v92, s29, v33
	v_add_u32_e32 v90, s28, v38
	s_cmp_lg_u32 s16, 0
	v_mad_u64_u32 v[62:63], s[28:29], v62, s83, v[6:7]
	v_mad_u64_u32 v[64:65], s[28:29], v64, s83, v[6:7]
	v_mad_u64_u32 v[66:67], s[28:29], v66, s83, v[6:7]
	v_mad_u64_u32 v[68:69], s[28:29], v68, s83, v[6:7]
	v_mad_u64_u32 v[70:71], s[28:29], v70, s83, v[6:7]
	v_mad_u64_u32 v[72:73], s[28:29], v72, s83, v[6:7]
	v_mad_u64_u32 v[74:75], s[28:29], v74, s83, v[6:7]
	v_mad_u64_u32 v[76:77], s[28:29], v76, s83, v[6:7]
	v_mad_u64_u32 v[78:79], s[28:29], v78, s83, v[6:7]
	v_mad_u64_u32 v[80:81], s[28:29], v80, s83, v[6:7]
	v_mad_u64_u32 v[82:83], s[28:29], v82, s83, v[6:7]
	v_mad_u64_u32 v[84:85], s[28:29], v84, s83, v[6:7]
	v_mad_u64_u32 v[86:87], s[28:29], v86, s83, v[6:7]
	v_mad_u64_u32 v[88:89], s[28:29], v88, s83, v[6:7]
	v_mad_u64_u32 v[90:91], s[28:29], v90, s83, v[6:7]
	v_mad_u64_u32 v[92:93], s[28:29], v92, s83, v[6:7]
	s_lshl_b32 s28, s13, 1
	s_lshl_b32 s29, s2, 1
	v_add_u32_e32 v120, s28, v42
	v_add_u32_e32 v118, s29, v35
	v_add_u32_e32 v122, s29, v37
	v_add_u32_e32 v124, s28, v44
	v_add_u32_e32 v126, s29, v39
	v_add_u32_e32 v128, s28, v46
	v_add_u32_e32 v130, s29, v43
	v_add_u32_e32 v132, s28, v48
	v_add_u32_e32 v134, s29, v45
	v_add_u32_e32 v136, s28, v50
	v_add_u32_e32 v138, s29, v47
	v_add_u32_e32 v140, s28, v52
	v_add_u32_e32 v142, s29, v49
	v_add_u32_e32 v144, s28, v54
	v_add_u32_e32 v146, s29, v51
	v_add_u32_e32 v148, s28, v56
	v_ashrrev_i32_e32 v121, 31, v120
	v_ashrrev_i32_e32 v119, 31, v118
	v_ashrrev_i32_e32 v125, 31, v124
	v_ashrrev_i32_e32 v123, 31, v122
	v_ashrrev_i32_e32 v129, 31, v128
	v_ashrrev_i32_e32 v127, 31, v126
	v_ashrrev_i32_e32 v133, 31, v132
	v_ashrrev_i32_e32 v131, 31, v130
	v_ashrrev_i32_e32 v137, 31, v136
	v_ashrrev_i32_e32 v135, 31, v134
	v_ashrrev_i32_e32 v141, 31, v140
	v_ashrrev_i32_e32 v139, 31, v138
	v_ashrrev_i32_e32 v145, 31, v144
	v_ashrrev_i32_e32 v143, 31, v142
	v_ashrrev_i32_e32 v149, 31, v148
	v_ashrrev_i32_e32 v147, 31, v146
	v_lshlrev_b64 v[120:121], 12, v[120:121]
	v_lshlrev_b64 v[118:119], 12, v[118:119]
	v_lshlrev_b64 v[122:123], 12, v[122:123]
	v_lshlrev_b64 v[124:125], 12, v[124:125]
; #define LAS __attribute__((address_space(3)))
; __device__ __forceinline__ unsigned pk2(float lo, float hi) { return pg8::cvt_pk_bf16(lo, hi); }
; #define LDS_WAIT() asm volatile("s_waitcnt lgkmcnt(0)" ::: "memory")
; template <int MODE> __device__ __forceinline__ void transpose_item(const float* __restrict__ W, int N, bf16_t* __restrict__ WT, int ldk, LAS float* scr, int item, int lane) {
;     ...
;     for (int i = 0; i < 32; ++i) { const int kk = 2 * i + (lane >> 5); scr[kk * 33 + (lane & 31)] = W[(size_t)(k0 + kk) * N + n0 + (lane & 31)]; }
;     LDS_WAIT();
;     const int c = lane & 7, r0 = dest_row<MODE>(n0);
; #pragma unroll
;     for (int j = 0; j < 4; ++j) { const int n = (lane >> 3) + 8 * j; const LAS float* s = scr + (8 * c) * 33 + n;
;         u32x4 o; o.x = pk2(s[0 * 33], s[1 * 33]); o.y = pk2(s[2 * 33], s[3 * 33]); o.z = pk2(s[4 * 33], s[5 * 33]); o.w = pk2(s[6 * 33], s[7 * 33]);
;         *(u32x4*)(WT + (size_t)(r0 + n) * ldk + k0 + 8 * c) = o; }
;     LDS_WAIT();
	v_lshlrev_b64 v[126:127], 12, v[126:127]
	v_lshlrev_b64 v[128:129], 12, v[128:129]
	v_lshlrev_b64 v[130:131], 12, v[130:131]
	v_lshlrev_b64 v[132:133], 12, v[132:133]
	v_lshlrev_b64 v[134:135], 12, v[134:135]
	v_lshlrev_b64 v[136:137], 12, v[136:137]
	v_lshlrev_b64 v[138:139], 12, v[138:139]
	v_lshlrev_b64 v[140:141], 12, v[140:141]
	v_lshlrev_b64 v[142:143], 12, v[142:143]
	v_lshlrev_b64 v[144:145], 12, v[144:145]
	v_lshlrev_b64 v[146:147], 12, v[146:147]
	v_lshlrev_b64 v[148:149], 12, v[148:149]
	v_lshl_add_u64 v[120:121], v[40:41], 0, v[120:121]
	v_lshl_add_u64 v[118:119], v[40:41], 0, v[118:119]
	v_lshl_add_u64 v[124:125], v[40:41], 0, v[124:125]
	v_lshl_add_u64 v[122:123], v[40:41], 0, v[122:123]
	v_lshl_add_u64 v[128:129], v[40:41], 0, v[128:129]
	v_lshl_add_u64 v[126:127], v[40:41], 0, v[126:127]
	v_lshl_add_u64 v[132:133], v[40:41], 0, v[132:133]
	v_lshl_add_u64 v[130:131], v[40:41], 0, v[130:131]
	v_lshl_add_u64 v[136:137], v[40:41], 0, v[136:137]
	v_lshl_add_u64 v[134:135], v[40:41], 0, v[134:135]
	v_lshl_add_u64 v[140:141], v[40:41], 0, v[140:141]
	v_lshl_add_u64 v[138:139], v[40:41], 0, v[138:139]
	v_lshl_add_u64 v[144:145], v[40:41], 0, v[144:145]
	v_lshl_add_u64 v[142:143], v[40:41], 0, v[142:143]
	v_lshl_add_u64 v[148:149], v[40:41], 0, v[148:149]
	v_lshl_add_u64 v[146:147], v[40:41], 0, v[146:147]
	global_load_dword v117, v[120:121], off
	global_load_dword v150, v[118:119], off
	global_load_dword v151, v[124:125], off
	global_load_dword v152, v[122:123], off
	global_load_dword v153, v[128:129], off
	global_load_dword v154, v[126:127], off
	global_load_dword v155, v[132:133], off
	global_load_dword v156, v[130:131], off
	global_load_dword v157, v[136:137], off
	global_load_dword v158, v[134:135], off
	global_load_dword v159, v[140:141], off
	global_load_dword v160, v[138:139], off
	global_load_dword v161, v[144:145], off
	global_load_dword v162, v[142:143], off
	global_load_dword v163, v[148:149], off
	global_load_dword v164, v[146:147], off
	s_add_i32 s13, s13, 16
	s_add_i32 s2, s2, 16
	s_add_i32 s16, s16, -16
	v_add_u32_e32 v118, s28, v2
	v_add_u32_e32 v120, s29, v1
	v_add_u32_e32 v124, s29, v3
	v_add_u32_e32 v122, s28, v26
	v_add_u32_e32 v128, s29, v5
	v_add_u32_e32 v126, s28, v28
	v_add_u32_e32 v132, s29, v7
	v_add_u32_e32 v130, s28, v30
	v_add_u32_e32 v136, s29, v27
	v_add_u32_e32 v134, s28, v32
	v_add_u32_e32 v140, s29, v29
	v_add_u32_e32 v138, s28, v34
	v_add_u32_e32 v144, s29, v31
	v_add_u32_e32 v142, s28, v36
	v_add_u32_e32 v148, s29, v33
	v_add_u32_e32 v146, s28, v38
	s_cmp_lg_u32 s16, 0
	v_mad_u64_u32 v[118:119], s[28:29], v118, s83, v[6:7]
	v_mad_u64_u32 v[120:121], s[28:29], v120, s83, v[6:7]
	v_mad_u64_u32 v[122:123], s[28:29], v122, s83, v[6:7]
	v_mad_u64_u32 v[124:125], s[28:29], v124, s83, v[6:7]
	v_mad_u64_u32 v[126:127], s[28:29], v126, s83, v[6:7]
	v_mad_u64_u32 v[128:129], s[28:29], v128, s83, v[6:7]
	v_mad_u64_u32 v[130:131], s[28:29], v130, s83, v[6:7]
	v_mad_u64_u32 v[132:133], s[28:29], v132, s83, v[6:7]
	v_mad_u64_u32 v[134:135], s[28:29], v134, s83, v[6:7]
	v_mad_u64_u32 v[136:137], s[28:29], v136, s83, v[6:7]
	v_mad_u64_u32 v[138:139], s[28:29], v138, s83, v[6:7]
	v_mad_u64_u32 v[140:141], s[28:29], v140, s83, v[6:7]
	v_mad_u64_u32 v[142:143], s[28:29], v142, s83, v[6:7]
	v_mad_u64_u32 v[144:145], s[28:29], v144, s83, v[6:7]
	v_mad_u64_u32 v[146:147], s[28:29], v146, s83, v[6:7]
	v_mad_u64_u32 v[148:149], s[28:29], v148, s83, v[6:7]
	s_waitcnt vmcnt(16)
	ds_write_b32 v62, v61
	ds_write_b32 v64, v94
	ds_write_b32 v66, v95
	ds_write_b32 v68, v96
	ds_write_b32 v70, v97
	ds_write_b32 v72, v98
	ds_write_b32 v74, v99
	ds_write_b32 v76, v100
	ds_write_b32 v78, v101
	ds_write_b32 v80, v102
	ds_write_b32 v82, v103
	ds_write_b32 v84, v104
	ds_write_b32 v86, v105
	ds_write_b32 v88, v106
	ds_write_b32 v90, v107
	ds_write_b32 v92, v108
	s_waitcnt vmcnt(0)
	ds_write_b32 v118, v117
	ds_write_b32 v120, v150
	ds_write_b32 v122, v151
	ds_write_b32 v124, v152
	ds_write_b32 v126, v153
	ds_write_b32 v128, v154
	ds_write_b32 v130, v155
	ds_write_b32 v132, v156
	ds_write_b32 v134, v157
	ds_write_b32 v136, v158
	ds_write_b32 v138, v159
	ds_write_b32 v140, v160
	ds_write_b32 v142, v161
	ds_write_b32 v144, v162
	ds_write_b32 v146, v163
	ds_write_b32 v148, v164
	s_waitcnt lgkmcnt(0)
	ds_read2_b32 v[44:45], v57 offset0:33 offset1:41
	ds_read2_b32 v[46:47], v57 offset1:8
	ds_read2_b32 v[48:49], v57 offset0:66 offset1:74
	ds_read2_b32 v[50:51], v57 offset0:99 offset1:107
	ds_read2_b32 v[62:63], v57 offset0:132 offset1:140
	ds_read2_b32 v[64:65], v57 offset0:165 offset1:173
	ds_read2_b32 v[66:67], v57 offset0:198 offset1:206
	ds_read2_b32 v[68:69], v57 offset0:231 offset1:239
	s_and_b32 s12, 0xffff, s12
	s_lshl_b32 s16, s3, 1
	v_lshl_add_u64 v[70:71], v[20:21], 0, s[16:17]
	v_add_u32_e32 v35, s12, v55
	s_waitcnt lgkmcnt(6)
	v_cvt_pk_f16_f32 v40, v46, v44
	s_waitcnt lgkmcnt(4)
	v_cvt_pk_f16_f32 v41, v48, v50
	s_waitcnt lgkmcnt(2)
	v_cvt_pk_f16_f32 v42, v62, v64
	s_waitcnt lgkmcnt(0)
	v_cvt_pk_f16_f32 v43, v66, v68
	v_mad_i64_i32 v[72:73], s[2:3], v35, s81, v[70:71]
	global_store_dwordx4 v[72:73], v[40:43], off
	v_add_u32_e32 v35, s12, v58
	s_nop 0
	v_cvt_pk_f16_f32 v40, v47, v45
	v_cvt_pk_f16_f32 v41, v49, v51
	v_cvt_pk_f16_f32 v42, v63, v65
	v_cvt_pk_f16_f32 v43, v67, v69
	ds_read2_b32 v[46:47], v57 offset0:49 offset1:57
	ds_read2_b32 v[48:49], v57 offset0:16 offset1:24
	ds_read2_b32 v[50:51], v57 offset0:82 offset1:90
	ds_read2_b32 v[62:63], v57 offset0:115 offset1:123
	ds_read2_b32 v[64:65], v57 offset0:148 offset1:156
	ds_read2_b32 v[66:67], v57 offset0:181 offset1:189
	ds_read2_b32 v[68:69], v57 offset0:214 offset1:222
	ds_read2_b32 v[72:73], v57 offset0:247 offset1:255
	v_mad_i64_i32 v[44:45], s[2:3], v35, s81, v[70:71]
	v_add_u32_e32 v35, s12, v59
	global_store_dwordx4 v[44:45], v[40:43], off
	v_mad_i64_i32 v[44:45], s[2:3], v35, s81, v[70:71]
	s_waitcnt lgkmcnt(6)
	v_cvt_pk_f16_f32 v40, v48, v46
	s_waitcnt lgkmcnt(4)
	v_cvt_pk_f16_f32 v41, v50, v62
	s_waitcnt lgkmcnt(2)
	v_cvt_pk_f16_f32 v42, v64, v66
	s_waitcnt lgkmcnt(0)
	v_cvt_pk_f16_f32 v43, v68, v72
	v_add_u32_e32 v35, s12, v60
	global_store_dwordx4 v[44:45], v[40:43], off
	v_mad_i64_i32 v[44:45], s[2:3], v35, s81, v[70:71]
	s_nop 0
	v_cvt_pk_f16_f32 v40, v49, v47
	v_cvt_pk_f16_f32 v41, v51, v63
	v_cvt_pk_f16_f32 v42, v65, v67
	v_cvt_pk_f16_f32 v43, v69, v73
	global_store_dwordx4 v[44:45], v[40:43], off
	s_waitcnt lgkmcnt(0)

; template <int MODE> __device__ __forceinline__ void transpose_item(const float* __restrict__ W, int N, bf16_t* __restrict__ WT, int ldk, LAS float* scr, int item, int lane) {
;     const int nblk = N / 32, kb = item / nblk, nb = item % nblk, k0 = 64 * kb, n0 = 32 * nb;
; #pragma unroll 8
;     for (int i = 0; i < 32; ++i) { const int kk = 2 * i + (lane >> 5); scr[kk * 33 + (lane & 31)] = W[(size_t)(k0 + kk) * N + n0 + (lane & 31)]; }
.LBB0_1069:
	s_lshl_b32 s29, s16, 1
	s_lshl_b32 s38, s13, 1
	v_add_u32_e32 v62, s29, v42
	v_add_u32_e32 v61, s38, v35
	v_add_u32_e32 v68, s38, v37
	v_add_u32_e32 v66, s29, v44
	v_add_u32_e32 v72, s38, v39
	v_add_u32_e32 v70, s29, v46
	v_add_u32_e32 v76, s38, v43
	v_add_u32_e32 v74, s29, v48
	v_add_u32_e32 v80, s38, v45
	v_add_u32_e32 v78, s29, v50
	v_add_u32_e32 v84, s38, v47
	v_add_u32_e32 v82, s29, v52
	v_add_u32_e32 v88, s38, v49
	v_add_u32_e32 v86, s29, v54
	v_add_u32_e32 v92, s38, v51
	v_add_u32_e32 v90, s29, v56
	v_mad_i64_i32 v[62:63], s[34:35], v62, s88, v[40:41]
	v_mad_i64_i32 v[64:65], s[34:35], v61, s88, v[40:41]
	v_mad_i64_i32 v[66:67], s[34:35], v66, s88, v[40:41]
	v_mad_i64_i32 v[68:69], s[34:35], v68, s88, v[40:41]
	v_mad_i64_i32 v[70:71], s[34:35], v70, s88, v[40:41]
	v_mad_i64_i32 v[72:73], s[34:35], v72, s88, v[40:41]
	v_mad_i64_i32 v[74:75], s[34:35], v74, s88, v[40:41]
	v_mad_i64_i32 v[76:77], s[34:35], v76, s88, v[40:41]
	v_mad_i64_i32 v[78:79], s[34:35], v78, s88, v[40:41]
	v_mad_i64_i32 v[80:81], s[34:35], v80, s88, v[40:41]
	v_mad_i64_i32 v[82:83], s[34:35], v82, s88, v[40:41]
	v_mad_i64_i32 v[84:85], s[34:35], v84, s88, v[40:41]
	v_mad_i64_i32 v[86:87], s[34:35], v86, s88, v[40:41]
	v_mad_i64_i32 v[88:89], s[34:35], v88, s88, v[40:41]
	v_mad_i64_i32 v[90:91], s[34:35], v90, s88, v[40:41]
	v_mad_i64_i32 v[92:93], s[34:35], v92, s88, v[40:41]
	global_load_dword v61, v[62:63], off
	global_load_dword v94, v[64:65], off
	global_load_dword v95, v[66:67], off
	global_load_dword v96, v[68:69], off
	global_load_dword v97, v[70:71], off
	global_load_dword v98, v[72:73], off
	global_load_dword v99, v[74:75], off
	global_load_dword v100, v[76:77], off
	global_load_dword v101, v[78:79], off
	global_load_dword v102, v[80:81], off
	global_load_dword v103, v[82:83], off
	global_load_dword v104, v[84:85], off
	global_load_dword v105, v[86:87], off
	global_load_dword v106, v[88:89], off
	global_load_dword v107, v[90:91], off
	global_load_dword v108, v[92:93], off
	s_add_i32 s16, s16, 16
	s_add_i32 s13, s13, 16
	s_add_i32 s28, s28, -16
	v_add_u32_e32 v62, s29, v2
	v_add_u32_e32 v64, s38, v1
	v_add_u32_e32 v68, s38, v3
	v_add_u32_e32 v66, s29, v26
	v_add_u32_e32 v72, s38, v5
	v_add_u32_e32 v70, s29, v28
	v_add_u32_e32 v76, s38, v7
	v_add_u32_e32 v74, s29, v30
	v_add_u32_e32 v80, s38, v27
	v_add_u32_e32 v78, s29, v32
	v_add_u32_e32 v84, s38, v29
	v_add_u32_e32 v82, s29, v34
	v_add_u32_e32 v88, s38, v31
	v_add_u32_e32 v86, s29, v36
	v_add_u32_e32 v92, s38, v33
	v_add_u32_e32 v90, s29, v38
	s_cmp_lg_u32 s28, 0
	v_mad_u64_u32 v[62:63], s[34:35], v62, s83, v[6:7]
	v_mad_u64_u32 v[64:65], s[34:35], v64, s83, v[6:7]
	v_mad_u64_u32 v[66:67], s[34:35], v66, s83, v[6:7]
	v_mad_u64_u32 v[68:69], s[34:35], v68, s83, v[6:7]
	v_mad_u64_u32 v[70:71], s[34:35], v70, s83, v[6:7]
	v_mad_u64_u32 v[72:73], s[34:35], v72, s83, v[6:7]
	v_mad_u64_u32 v[74:75], s[34:35], v74, s83, v[6:7]
	v_mad_u64_u32 v[76:77], s[34:35], v76, s83, v[6:7]
	v_mad_u64_u32 v[78:79], s[34:35], v78, s83, v[6:7]
	v_mad_u64_u32 v[80:81], s[34:35], v80, s83, v[6:7]
	v_mad_u64_u32 v[82:83], s[34:35], v82, s83, v[6:7]
	v_mad_u64_u32 v[84:85], s[34:35], v84, s83, v[6:7]
	v_mad_u64_u32 v[86:87], s[34:35], v86, s83, v[6:7]
	v_mad_u64_u32 v[88:89], s[34:35], v88, s83, v[6:7]
	v_mad_u64_u32 v[90:91], s[34:35], v90, s83, v[6:7]
	v_mad_u64_u32 v[92:93], s[34:35], v92, s83, v[6:7]
	s_lshl_b32 s29, s16, 1
	s_lshl_b32 s38, s13, 1
	v_add_u32_e32 v118, s29, v42
	v_add_u32_e32 v117, s38, v35
	v_add_u32_e32 v124, s38, v37
	v_add_u32_e32 v122, s29, v44
	v_add_u32_e32 v128, s38, v39
	v_add_u32_e32 v126, s29, v46
	v_add_u32_e32 v132, s38, v43
	v_add_u32_e32 v130, s29, v48
	v_add_u32_e32 v136, s38, v45
	v_add_u32_e32 v134, s29, v50
	v_add_u32_e32 v140, s38, v47
	v_add_u32_e32 v138, s29, v52
	v_add_u32_e32 v144, s38, v49
	v_add_u32_e32 v142, s29, v54
	v_add_u32_e32 v148, s38, v51
	v_add_u32_e32 v146, s29, v56
	v_mad_i64_i32 v[118:119], s[34:35], v118, s88, v[40:41]
	v_mad_i64_i32 v[120:121], s[34:35], v117, s88, v[40:41]
	v_mad_i64_i32 v[122:123], s[34:35], v122, s88, v[40:41]
	v_mad_i64_i32 v[124:125], s[34:35], v124, s88, v[40:41]
	v_mad_i64_i32 v[126:127], s[34:35], v126, s88, v[40:41]
	v_mad_i64_i32 v[128:129], s[34:35], v128, s88, v[40:41]
	v_mad_i64_i32 v[130:131], s[34:35], v130, s88, v[40:41]
	v_mad_i64_i32 v[132:133], s[34:35], v132, s88, v[40:41]
	v_mad_i64_i32 v[134:135], s[34:35], v134, s88, v[40:41]
	v_mad_i64_i32 v[136:137], s[34:35], v136, s88, v[40:41]
	v_mad_i64_i32 v[138:139], s[34:35], v138, s88, v[40:41]
	v_mad_i64_i32 v[140:141], s[34:35], v140, s88, v[40:41]
	v_mad_i64_i32 v[142:143], s[34:35], v142, s88, v[40:41]
	v_mad_i64_i32 v[144:145], s[34:35], v144, s88, v[40:41]
	v_mad_i64_i32 v[146:147], s[34:35], v146, s88, v[40:41]
	v_mad_i64_i32 v[148:149], s[34:35], v148, s88, v[40:41]
	global_load_dword v117, v[118:119], off
	global_load_dword v150, v[120:121], off
	global_load_dword v151, v[122:123], off
	global_load_dword v152, v[124:125], off
	global_load_dword v153, v[126:127], off
	global_load_dword v154, v[128:129], off
	global_load_dword v155, v[130:131], off
	global_load_dword v156, v[132:133], off
	global_load_dword v157, v[134:135], off
	global_load_dword v158, v[136:137], off
	global_load_dword v159, v[138:139], off
	global_load_dword v160, v[140:141], off
	global_load_dword v161, v[142:143], off
	global_load_dword v162, v[144:145], off
	global_load_dword v163, v[146:147], off
	global_load_dword v164, v[148:149], off
	s_add_i32 s16, s16, 16
	s_add_i32 s13, s13, 16
	s_add_i32 s28, s28, -16
	v_add_u32_e32 v118, s29, v2
	v_add_u32_e32 v120, s38, v1
	v_add_u32_e32 v124, s38, v3
	v_add_u32_e32 v122, s29, v26
	v_add_u32_e32 v128, s38, v5
	v_add_u32_e32 v126, s29, v28
	v_add_u32_e32 v132, s38, v7
	v_add_u32_e32 v130, s29, v30
	v_add_u32_e32 v136, s38, v27
	v_add_u32_e32 v134, s29, v32
	v_add_u32_e32 v140, s38, v29
	v_add_u32_e32 v138, s29, v34
	v_add_u32_e32 v144, s38, v31
	v_add_u32_e32 v142, s29, v36
	v_add_u32_e32 v148, s38, v33
	v_add_u32_e32 v146, s29, v38
	s_cmp_lg_u32 s28, 0
	v_mad_u64_u32 v[118:119], s[34:35], v118, s83, v[6:7]
	v_mad_u64_u32 v[120:121], s[34:35], v120, s83, v[6:7]
	v_mad_u64_u32 v[122:123], s[34:35], v122, s83, v[6:7]
	v_mad_u64_u32 v[124:125], s[34:35], v124, s83, v[6:7]
	v_mad_u64_u32 v[126:127], s[34:35], v126, s83, v[6:7]
	v_mad_u64_u32 v[128:129], s[34:35], v128, s83, v[6:7]
	v_mad_u64_u32 v[130:131], s[34:35], v130, s83, v[6:7]
	v_mad_u64_u32 v[132:133], s[34:35], v132, s83, v[6:7]
	v_mad_u64_u32 v[134:135], s[34:35], v134, s83, v[6:7]
	v_mad_u64_u32 v[136:137], s[34:35], v136, s83, v[6:7]
	v_mad_u64_u32 v[138:139], s[34:35], v138, s83, v[6:7]
	v_mad_u64_u32 v[140:141], s[34:35], v140, s83, v[6:7]
	v_mad_u64_u32 v[142:143], s[34:35], v142, s83, v[6:7]
	v_mad_u64_u32 v[144:145], s[34:35], v144, s83, v[6:7]
	v_mad_u64_u32 v[146:147], s[34:35], v146, s83, v[6:7]
	v_mad_u64_u32 v[148:149], s[34:35], v148, s83, v[6:7]
	s_waitcnt vmcnt(16)
; #define LAS __attribute__((address_space(3)))
; __device__ __forceinline__ unsigned pk2(float lo, float hi) { return pg8::cvt_pk_bf16(lo, hi); }
; #define LDS_WAIT() asm volatile("s_waitcnt lgkmcnt(0)" ::: "memory")
; template <int MODE> __device__ __forceinline__ int dest_row(int n0) {
;     if (MODE == 1) { const int g = n0 >= DFF ? 1 : 0; const int nn = n0 - g * DFF; return (nn >> 7) * 256 + g * 128 + (nn & 127); }
;     return n0;
; }
; template <int MODE> __device__ __forceinline__ void transpose_item(const float* __restrict__ W, int N, bf16_t* __restrict__ WT, int ldk, LAS float* scr, int item, int lane) {
;     const int nblk = N / 32, kb = item / nblk, nb = item % nblk, k0 = 64 * kb, n0 = 32 * nb;
; #pragma unroll 8
;     for (int i = 0; i < 32; ++i) { const int kk = 2 * i + (lane >> 5); scr[kk * 33 + (lane & 31)] = W[(size_t)(k0 + kk) * N + n0 + (lane & 31)]; }
;     LDS_WAIT();
;     const int c = lane & 7, r0 = dest_row<MODE>(n0);
; #pragma unroll
;     for (int j = 0; j < 4; ++j) { const int n = (lane >> 3) + 8 * j; const LAS float* s = scr + (8 * c) * 33 + n;
;         u32x4 o; o.x = pk2(s[0 * 33], s[1 * 33]); o.y = pk2(s[2 * 33], s[3 * 33]); o.z = pk2(s[4 * 33], s[5 * 33]); o.w = pk2(s[6 * 33], s[7 * 33]);
;         *(u32x4*)(WT + (size_t)(r0 + n) * ldk + k0 + 8 * c) = o; }
;     LDS_WAIT();
	ds_write_b32 v62, v61
	ds_write_b32 v64, v94
	ds_write_b32 v66, v95
	ds_write_b32 v68, v96
	ds_write_b32 v70, v97
	ds_write_b32 v72, v98
	ds_write_b32 v74, v99
	ds_write_b32 v76, v100
	ds_write_b32 v78, v101
	ds_write_b32 v80, v102
	ds_write_b32 v82, v103
	ds_write_b32 v84, v104
	ds_write_b32 v86, v105
	ds_write_b32 v88, v106
	ds_write_b32 v90, v107
	ds_write_b32 v92, v108
	s_waitcnt vmcnt(0)
	ds_write_b32 v118, v117
	ds_write_b32 v120, v150
	ds_write_b32 v122, v151
	ds_write_b32 v124, v152
	ds_write_b32 v126, v153
	ds_write_b32 v128, v154
	ds_write_b32 v130, v155
	ds_write_b32 v132, v156
	ds_write_b32 v134, v157
	ds_write_b32 v136, v158
	ds_write_b32 v138, v159
	ds_write_b32 v140, v160
	ds_write_b32 v142, v161
	ds_write_b32 v144, v162
	ds_write_b32 v146, v163
	ds_write_b32 v148, v164
	s_and_b32 s12, 0xffff, s12
	s_and_b32 s3, 0xffff, s3
	s_cmpk_gt_u32 s3, 0x57
	s_cselect_b32 s3, 0xfffff500, 0
	s_cselect_b32 s13, 0x80, 0
	s_add_i32 s3, s3, s12
	s_waitcnt lgkmcnt(0)
	s_lshl_b32 s3, s3, 1
	s_and_b32 s12, s12, 0x60
	s_and_b32 s3, s3, 0xffffff00
	s_or_b32 s12, s12, s13
	ds_read2_b32 v[44:45], v57 offset0:33 offset1:41
	ds_read2_b32 v[46:47], v57 offset1:8
	ds_read2_b32 v[48:49], v57 offset0:66 offset1:74
	ds_read2_b32 v[50:51], v57 offset0:99 offset1:107
	ds_read2_b32 v[62:63], v57 offset0:132 offset1:140
	ds_read2_b32 v[64:65], v57 offset0:165 offset1:173
	ds_read2_b32 v[66:67], v57 offset0:198 offset1:206
	ds_read2_b32 v[68:69], v57 offset0:231 offset1:239
	s_or_b32 s3, s12, s3
	s_and_b32 s2, 0xffff, s2
	v_add_u32_e32 v72, s3, v55
	s_lshl_b32 s16, s2, 1
	v_ashrrev_i32_e32 v73, 31, v72
	v_lshl_add_u64 v[70:71], v[22:23], 0, s[16:17]
	v_lshlrev_b64 v[72:73], 11, v[72:73]
	s_waitcnt lgkmcnt(6)
	v_cvt_pk_f16_f32 v40, v46, v44
	s_waitcnt lgkmcnt(4)
	v_cvt_pk_f16_f32 v41, v48, v50
	s_waitcnt lgkmcnt(2)
	v_cvt_pk_f16_f32 v42, v62, v64
	s_waitcnt lgkmcnt(0)
	v_cvt_pk_f16_f32 v43, v66, v68
	v_lshl_add_u64 v[72:73], v[70:71], 0, v[72:73]
	v_add_u32_e32 v44, s3, v58
	global_store_dwordx4 v[72:73], v[40:43], off
	s_nop 1
	v_cvt_pk_f16_f32 v40, v47, v45
	v_ashrrev_i32_e32 v45, 31, v44
	v_cvt_pk_f16_f32 v41, v49, v51
	v_cvt_pk_f16_f32 v42, v63, v65
	v_cvt_pk_f16_f32 v43, v67, v69
	v_lshlrev_b64 v[44:45], 11, v[44:45]
	ds_read2_b32 v[46:47], v57 offset0:49 offset1:57
	ds_read2_b32 v[48:49], v57 offset0:16 offset1:24
	ds_read2_b32 v[50:51], v57 offset0:82 offset1:90
	ds_read2_b32 v[62:63], v57 offset0:115 offset1:123
	ds_read2_b32 v[64:65], v57 offset0:148 offset1:156
	ds_read2_b32 v[66:67], v57 offset0:181 offset1:189
	ds_read2_b32 v[68:69], v57 offset0:214 offset1:222
	ds_read2_b32 v[72:73], v57 offset0:247 offset1:255
	v_lshl_add_u64 v[44:45], v[70:71], 0, v[44:45]
	global_store_dwordx4 v[44:45], v[40:43], off
	v_add_u32_e32 v44, s3, v59
	v_ashrrev_i32_e32 v45, 31, v44
	v_lshlrev_b64 v[44:45], 11, v[44:45]
	s_waitcnt lgkmcnt(6)
	v_cvt_pk_f16_f32 v40, v48, v46
	s_waitcnt lgkmcnt(4)
	v_cvt_pk_f16_f32 v41, v50, v62
	s_waitcnt lgkmcnt(2)
	v_cvt_pk_f16_f32 v42, v64, v66
	s_waitcnt lgkmcnt(0)
	v_cvt_pk_f16_f32 v43, v68, v72
	v_lshl_add_u64 v[44:45], v[70:71], 0, v[44:45]
	global_store_dwordx4 v[44:45], v[40:43], off
	v_add_u32_e32 v44, s3, v60
	v_ashrrev_i32_e32 v45, 31, v44
	v_lshlrev_b64 v[44:45], 11, v[44:45]
	v_cvt_pk_f16_f32 v40, v49, v47
	v_cvt_pk_f16_f32 v41, v51, v63
	v_cvt_pk_f16_f32 v42, v65, v67
	v_cvt_pk_f16_f32 v43, v69, v73
	v_lshl_add_u64 v[44:45], v[70:71], 0, v[44:45]
	global_store_dwordx4 v[44:45], v[40:43], off
	s_waitcnt lgkmcnt(0)
